# v36 with per-block s_setprio toggling removed from all GEMM loops; one static s_setprio 1 for the trailing wave half (waves 4-7) from the in-proj phase on
# speedup vs baseline: 1.0049x; 1.0031x over previous
.LBB0_218:
	s_add_u32 s6, s74, 0x200000
	s_addc_u32 s7, s75, 0
	s_and_b32 s8, s16, 3
	s_lshl_b32 s61, s8, 5
	s_lshl_b32 s17, s8, 12
	s_mov_b64 s[8:9], 0x80
	s_add_i32 m0, s56, 0x18000
	v_lshl_add_u64 v[8:9], v[8:9], 0, s[8:9]
	s_lshl_b32 s11, s10, 13
	s_waitcnt vmcnt(2)
	s_barrier
	global_load_lds_dwordx4 v[8:9], off
	v_lshl_add_u64 v[6:7], v[6:7], 0, s[8:9]
	s_add_i32 m0, s56, 0x1a000
	s_add_i32 s62, s56, 0x8000
	s_add_i32 s63, s56, 0xa000
	global_load_lds_dwordx4 v[6:7], off
	v_lshl_add_u64 v[2:3], v[2:3], 0, s[8:9]
	s_mov_b32 m0, s62
	s_add_u32 s18, s52, 0x100080
	global_load_lds_dwordx4 v[2:3], off
	v_lshl_add_u64 v[2:3], v[4:5], 0, s[8:9]
	s_mov_b32 m0, s63
	s_addc_u32 s19, s53, 0
	global_load_lds_dwordx4 v[2:3], off
	s_add_i32 m0, s56, 0x1c000
	v_lshl_add_u64 v[2:3], s[18:19], 0, v[182:183]
	global_load_lds_dwordx4 v[2:3], off
	v_lshl_add_u64 v[2:3], s[18:19], 0, v[178:179]
	s_add_i32 m0, s56, 0x1e000
	v_lshlrev_b32_e32 v5, 2, v0
	global_load_lds_dwordx4 v[2:3], off
	v_bfe_u32 v3, v0, 4, 2
	v_and_b32_e32 v2, 15, v0
	v_lshlrev_b32_e32 v4, 4, v3
	s_sext_i32_i16 s84, s2
	v_lshl_or_b32 v1, s10, 6, v2
	v_lshl_or_b32 v2, v2, 6, v4
	v_and_b32_e32 v5, 32, v5
	v_lshlrev_b32_e32 v6, 6, v0
	s_movk_i32 s2, 0x3c0
	s_cmpk_lt_u32 s3, 0x100
	v_lshlrev_b32_e32 v188, 3, v3
	v_bitop3_b32 v2, v2, s11, v5 bitop3:0xde
	v_and_or_b32 v4, v6, s2, v4
	s_cselect_b64 s[10:11], -1, 0
	s_lshl_b32 s2, s16, 4
	v_lshlrev_b32_e32 v3, 2, v3
	v_and_or_b32 v207, s2, 16, v3
	v_lshlrev_b32_e32 v3, 10, v0
	v_bitop3_b32 v189, s17, v4, v5 bitop3:0xf6
	v_and_b32_e32 v3, 0x60000, v3
	v_lshlrev_b32_e32 v4, 13, v14
	v_or3_b32 v3, v11, v3, v4
	s_ashr_i32 s64, s33, 31
	v_add_u32_e32 v192, v3, v12
	v_lshlrev_b32_e32 v3, 6, v10
	s_waitcnt vmcnt(6)
	s_add_u32 s2, s74, s61
	v_and_b32_e32 v3, 0xe0000, v3
	s_addc_u32 s3, s75, 0
	v_and_b32_e32 v186, 16, v13
	v_or3_b32 v3, v11, v3, v4
	s_add_i32 s65, 0, 0x10000
	s_add_i32 s66, 0, 0x14000
	v_and_b32_e32 v206, 16, v0
	v_lshl_add_u64 v[190:191], s[2:3], 0, v[186:187]
	v_mov_b32_e32 v193, v187
	v_add_u32_e32 v194, v3, v12
	v_mov_b32_e32 v195, v187
	v_mov_b64_e32 v[196:197], 0x600
	v_mov_b64_e32 v[198:199], 0x5ff
	v_add_u32_e32 v208, s65, v189
	v_add_u32_e32 v209, s66, v189
	v_add_u32_e32 v210, 0, v2
	s_mov_b64 s[16:17], 0x80000
	s_mov_b32 s67, 0x80000
	s_mov_b64 s[18:19], 0xa0000
	s_mov_b32 s76, 0xa0000
	s_mov_b64 s[20:21], 0x90000
	s_mov_b32 s77, 0x90000
	s_mov_b64 s[22:23], 0xb0000
	s_mov_b32 s80, 0xb0000
	s_mov_b32 s81, 0xf9e0
	s_mov_b64 s[24:25], 0x1000
	s_mov_b64 s[26:27], 0x2000
	s_mov_b64 s[38:39], 0x3000
	s_movk_i32 s82, 0x3000
	v_mov_b32_e32 v211, 0x3e38aa3b
	s_mov_b32 s83, 0
	s_cmp_lt_u32 s79, 4
	s_cbranch_scc1 .Lgemm_prio_skip
	s_setprio 1
.Lgemm_prio_skip:
	s_barrier
	s_branch .LBB0_221

.Lpeela:
	ds_read_b128 v[130:133], v208
	ds_read_b128 v[134:137], v208 offset:1024
	ds_read_b128 v[138:141], v208 offset:2048
	ds_read_b128 v[142:145], v208 offset:3072
	ds_read_b128 v[146:149], v209
	ds_read_b128 v[150:153], v209 offset:1024
	ds_read_b128 v[154:157], v209 offset:2048
	ds_read_b128 v[158:161], v209 offset:3072
	s_add_u32 s52, s50, 0xfff00080
	s_addc_u32 s53, s51, -1
	s_cmp_eq_u32 s89, 60
	s_cselect_b32 s55, s43, s53
	s_cselect_b32 s54, s85, s52
	s_cselect_b32 s53, s41, s88
	s_cselect_b32 s52, s86, s87
	v_lshl_add_u64 v[204:205], s[50:51], 0, v[192:193]
	s_add_i32 m0, s56, 0xc000
	ds_read_b128 v[162:165], v210
	ds_read_b128 v[166:169], v210 offset:1024
	ds_read_b128 v[170:173], v210 offset:2048
	ds_read_b128 v[174:177], v210 offset:3072
	ds_read_b128 v[200:203], v210 offset:4096
	ds_read_b128 v[212:215], v210 offset:5120
	ds_read_b128 v[216:219], v210 offset:6144
	ds_read_b128 v[224:227], v210 offset:7168
	global_load_lds_dwordx4 v[204:205], off
	v_lshl_add_u64 v[204:205], s[50:51], 0, v[194:195]
	s_add_i32 m0, s56, 0xe000
	s_nop 0
	global_load_lds_dwordx4 v[204:205], off
	s_waitcnt vmcnt(8)
	s_waitcnt lgkmcnt(0)
	s_barrier
	v_mfma_f32_16x16x32_bf16 v[126:129], v[130:133], v[162:165], 0
	v_mfma_f32_16x16x32_bf16 v[122:125], v[138:141], v[162:165], 0
	v_mfma_f32_16x16x32_bf16 v[110:113], v[130:133], v[170:173], 0
	v_mfma_f32_16x16x32_bf16 v[106:109], v[138:141], v[170:173], 0
	v_mfma_f32_16x16x32_bf16 v[94:97], v[130:133], v[200:203], 0
	v_mfma_f32_16x16x32_bf16 v[90:93], v[138:141], v[200:203], 0
	v_mfma_f32_16x16x32_bf16 v[78:81], v[130:133], v[216:219], 0
	v_mfma_f32_16x16x32_bf16 v[74:77], v[138:141], v[216:219], 0
	v_mfma_f32_16x16x32_bf16 v[126:129], v[134:137], v[166:169], v[126:129]
	v_mfma_f32_16x16x32_bf16 v[122:125], v[142:145], v[166:169], v[122:125]
	v_mfma_f32_16x16x32_bf16 v[110:113], v[134:137], v[174:177], v[110:113]
	v_mfma_f32_16x16x32_bf16 v[106:109], v[142:145], v[174:177], v[106:109]
	v_mfma_f32_16x16x32_bf16 v[94:97], v[134:137], v[212:215], v[94:97]
	v_mfma_f32_16x16x32_bf16 v[90:93], v[142:145], v[212:215], v[90:93]
	v_mfma_f32_16x16x32_bf16 v[78:81], v[134:137], v[224:227], v[78:81]
	v_mfma_f32_16x16x32_bf16 v[74:77], v[142:145], v[224:227], v[74:77]
	v_mfma_f32_16x16x32_bf16 v[118:121], v[146:149], v[162:165], 0
	v_mfma_f32_16x16x32_bf16 v[114:117], v[154:157], v[162:165], 0
	v_mfma_f32_16x16x32_bf16 v[102:105], v[146:149], v[170:173], 0
	v_mfma_f32_16x16x32_bf16 v[98:101], v[154:157], v[170:173], 0
	v_mfma_f32_16x16x32_bf16 v[86:89], v[146:149], v[200:203], 0
	v_mfma_f32_16x16x32_bf16 v[82:85], v[154:157], v[200:203], 0
	v_mfma_f32_16x16x32_bf16 v[70:73], v[146:149], v[216:219], 0
	v_mfma_f32_16x16x32_bf16 v[66:69], v[154:157], v[216:219], 0
	v_mfma_f32_16x16x32_bf16 v[118:121], v[150:153], v[166:169], v[118:121]
	v_mfma_f32_16x16x32_bf16 v[114:117], v[158:161], v[166:169], v[114:117]
	v_mfma_f32_16x16x32_bf16 v[102:105], v[150:153], v[174:177], v[102:105]
	v_mfma_f32_16x16x32_bf16 v[98:101], v[158:161], v[174:177], v[98:101]
	v_mfma_f32_16x16x32_bf16 v[86:89], v[150:153], v[212:215], v[86:89]
	v_mfma_f32_16x16x32_bf16 v[82:85], v[158:161], v[212:215], v[82:85]
	v_mfma_f32_16x16x32_bf16 v[70:73], v[150:153], v[224:227], v[70:73]
	v_mfma_f32_16x16x32_bf16 v[66:69], v[158:161], v[224:227], v[66:69]
	s_barrier
	s_add_i32 s90, s65, s31
	v_lshl_add_u64 v[204:205], s[52:53], 0, v[182:183]
	s_mov_b32 m0, s90
	ds_read_b128 v[162:165], v210 offset:16384
	ds_read_b128 v[166:169], v210 offset:17408
	ds_read_b128 v[170:173], v210 offset:18432
	ds_read_b128 v[174:177], v210 offset:19456
	ds_read_b128 v[200:203], v210 offset:20480
	ds_read_b128 v[212:215], v210 offset:21504
	ds_read_b128 v[216:219], v210 offset:22528
	ds_read_b128 v[224:227], v210 offset:23552
	global_load_lds_dwordx4 v[204:205], off
	s_add_i32 m0, s90, 0x2000
	s_add_u32 s90, s52, 0x100000
	v_lshl_add_u64 v[220:221], s[52:53], 0, v[178:179]
	s_addc_u32 s91, s53, 0
	s_add_i32 s92, s66, s31
	global_load_lds_dwordx4 v[220:221], off
	v_lshl_add_u64 v[228:229], s[90:91], 0, v[182:183]
	s_mov_b32 m0, s92
	v_lshl_add_u64 v[230:231], s[54:55], 0, v[180:181]
	global_load_lds_dwordx4 v[228:229], off
	v_lshl_add_u64 v[228:229], s[90:91], 0, v[178:179]
	s_add_i32 m0, s92, 0x2000
	s_nop 0
	global_load_lds_dwordx4 v[228:229], off
	v_lshl_add_u64 v[228:229], s[54:55], 0, v[184:185]
	s_mov_b32 m0, s56
	s_nop 0
	global_load_lds_dwordx4 v[228:229], off
	s_mov_b32 m0, s57
	s_nop 0
	global_load_lds_dwordx4 v[230:231], off
	s_waitcnt vmcnt(8)
	s_waitcnt lgkmcnt(0)
	s_barrier
	v_mfma_f32_16x16x32_bf16 v[62:65], v[130:133], v[162:165], 0
	v_mfma_f32_16x16x32_bf16 v[58:61], v[138:141], v[162:165], 0
	v_mfma_f32_16x16x32_bf16 v[50:53], v[130:133], v[170:173], 0
	v_mfma_f32_16x16x32_bf16 v[42:45], v[138:141], v[170:173], 0
	v_mfma_f32_16x16x32_bf16 v[34:37], v[130:133], v[200:203], 0
	v_mfma_f32_16x16x32_bf16 v[26:29], v[138:141], v[200:203], 0
	v_mfma_f32_16x16x32_bf16 v[18:21], v[130:133], v[216:219], 0
	v_mfma_f32_16x16x32_bf16 v[10:13], v[138:141], v[216:219], 0
	v_mfma_f32_16x16x32_bf16 v[62:65], v[134:137], v[166:169], v[62:65]
	v_mfma_f32_16x16x32_bf16 v[58:61], v[142:145], v[166:169], v[58:61]
	v_mfma_f32_16x16x32_bf16 v[50:53], v[134:137], v[174:177], v[50:53]
	v_mfma_f32_16x16x32_bf16 v[42:45], v[142:145], v[174:177], v[42:45]
	v_mfma_f32_16x16x32_bf16 v[34:37], v[134:137], v[212:215], v[34:37]
	v_mfma_f32_16x16x32_bf16 v[26:29], v[142:145], v[212:215], v[26:29]
	v_mfma_f32_16x16x32_bf16 v[18:21], v[134:137], v[224:227], v[18:21]
	v_mfma_f32_16x16x32_bf16 v[10:13], v[142:145], v[224:227], v[10:13]
	v_mfma_f32_16x16x32_bf16 v[54:57], v[146:149], v[162:165], 0
	v_mfma_f32_16x16x32_bf16 v[46:49], v[154:157], v[162:165], 0
	v_mfma_f32_16x16x32_bf16 v[38:41], v[146:149], v[170:173], 0
	v_mfma_f32_16x16x32_bf16 v[30:33], v[154:157], v[170:173], 0
	v_mfma_f32_16x16x32_bf16 v[22:25], v[146:149], v[200:203], 0
	v_mfma_f32_16x16x32_bf16 v[14:17], v[154:157], v[200:203], 0
	v_mfma_f32_16x16x32_bf16 v[6:9], v[146:149], v[216:219], 0
	v_mfma_f32_16x16x32_bf16 v[2:5], v[154:157], v[216:219], 0
	v_mfma_f32_16x16x32_bf16 v[54:57], v[150:153], v[166:169], v[54:57]
	v_mfma_f32_16x16x32_bf16 v[46:49], v[158:161], v[166:169], v[46:49]
	v_mfma_f32_16x16x32_bf16 v[38:41], v[150:153], v[174:177], v[38:41]
	v_mfma_f32_16x16x32_bf16 v[30:33], v[158:161], v[174:177], v[30:33]
	v_mfma_f32_16x16x32_bf16 v[22:25], v[150:153], v[212:215], v[22:25]
	v_mfma_f32_16x16x32_bf16 v[14:17], v[158:161], v[212:215], v[14:17]
	v_mfma_f32_16x16x32_bf16 v[6:9], v[150:153], v[224:227], v[6:9]
	v_mfma_f32_16x16x32_bf16 v[2:5], v[158:161], v[224:227], v[2:5]
	s_barrier
	s_add_i32 s90, 0, 0x18000
	s_add_i32 s91, 0, 0x1c000
	v_add_u32_e32 v142, s90, v189
	v_add_u32_e32 v158, s91, v189
	ds_read_b128 v[130:133], v142
	ds_read_b128 v[134:137], v142 offset:1024
	ds_read_b128 v[138:141], v142 offset:2048
	ds_read_b128 v[142:145], v142 offset:3072
	ds_read_b128 v[146:149], v158
	ds_read_b128 v[150:153], v158 offset:1024
	ds_read_b128 v[154:157], v158 offset:2048
	ds_read_b128 v[158:161], v158 offset:3072
	s_add_u32 s54, s54, 0x100000
	s_addc_u32 s55, s55, 0
	s_mov_b32 m0, s58
	v_lshl_add_u64 v[232:233], s[54:55], 0, v[184:185]
	ds_read_b128 v[162:165], v210 offset:32768
	ds_read_b128 v[166:169], v210 offset:33792
	ds_read_b128 v[170:173], v210 offset:34816
	ds_read_b128 v[174:177], v210 offset:35840
	ds_read_b128 v[200:203], v210 offset:36864
	ds_read_b128 v[212:215], v210 offset:37888
	ds_read_b128 v[216:219], v210 offset:38912
	ds_read_b128 v[224:227], v210 offset:39936
	global_load_lds_dwordx4 v[232:233], off
	v_lshl_add_u64 v[232:233], s[54:55], 0, v[180:181]
	s_mov_b32 m0, s59
	s_nop 0
	global_load_lds_dwordx4 v[232:233], off
	s_waitcnt vmcnt(8)
	s_waitcnt lgkmcnt(0)
	s_barrier
	v_mfma_f32_16x16x32_bf16 v[126:129], v[130:133], v[162:165], v[126:129]
	v_mfma_f32_16x16x32_bf16 v[122:125], v[138:141], v[162:165], v[122:125]
	v_mfma_f32_16x16x32_bf16 v[110:113], v[130:133], v[170:173], v[110:113]
	v_mfma_f32_16x16x32_bf16 v[106:109], v[138:141], v[170:173], v[106:109]
	v_mfma_f32_16x16x32_bf16 v[94:97], v[130:133], v[200:203], v[94:97]
	v_mfma_f32_16x16x32_bf16 v[90:93], v[138:141], v[200:203], v[90:93]
	v_mfma_f32_16x16x32_bf16 v[78:81], v[130:133], v[216:219], v[78:81]
	v_mfma_f32_16x16x32_bf16 v[74:77], v[138:141], v[216:219], v[74:77]
	v_mfma_f32_16x16x32_bf16 v[126:129], v[134:137], v[166:169], v[126:129]
	v_mfma_f32_16x16x32_bf16 v[122:125], v[142:145], v[166:169], v[122:125]
	v_mfma_f32_16x16x32_bf16 v[110:113], v[134:137], v[174:177], v[110:113]
	v_mfma_f32_16x16x32_bf16 v[106:109], v[142:145], v[174:177], v[106:109]
	v_mfma_f32_16x16x32_bf16 v[94:97], v[134:137], v[212:215], v[94:97]
	v_mfma_f32_16x16x32_bf16 v[90:93], v[142:145], v[212:215], v[90:93]
	v_mfma_f32_16x16x32_bf16 v[78:81], v[134:137], v[224:227], v[78:81]
	v_mfma_f32_16x16x32_bf16 v[74:77], v[142:145], v[224:227], v[74:77]
	v_mfma_f32_16x16x32_bf16 v[118:121], v[146:149], v[162:165], v[118:121]
	v_mfma_f32_16x16x32_bf16 v[114:117], v[154:157], v[162:165], v[114:117]
	v_mfma_f32_16x16x32_bf16 v[102:105], v[146:149], v[170:173], v[102:105]
	v_mfma_f32_16x16x32_bf16 v[98:101], v[154:157], v[170:173], v[98:101]
	v_mfma_f32_16x16x32_bf16 v[86:89], v[146:149], v[200:203], v[86:89]
	v_mfma_f32_16x16x32_bf16 v[82:85], v[154:157], v[200:203], v[82:85]
	v_mfma_f32_16x16x32_bf16 v[70:73], v[146:149], v[216:219], v[70:73]
	v_mfma_f32_16x16x32_bf16 v[66:69], v[154:157], v[216:219], v[66:69]
	v_mfma_f32_16x16x32_bf16 v[118:121], v[150:153], v[166:169], v[118:121]
	v_mfma_f32_16x16x32_bf16 v[114:117], v[158:161], v[166:169], v[114:117]
	v_mfma_f32_16x16x32_bf16 v[102:105], v[150:153], v[174:177], v[102:105]
	v_mfma_f32_16x16x32_bf16 v[98:101], v[158:161], v[174:177], v[98:101]
	v_mfma_f32_16x16x32_bf16 v[86:89], v[150:153], v[212:215], v[86:89]
	v_mfma_f32_16x16x32_bf16 v[82:85], v[158:161], v[212:215], v[82:85]
	v_mfma_f32_16x16x32_bf16 v[70:73], v[150:153], v[224:227], v[70:73]
	v_mfma_f32_16x16x32_bf16 v[66:69], v[158:161], v[224:227], v[66:69]
	s_barrier
	s_add_i32 s54, s90, s31
	v_lshl_add_u64 v[204:205], v[204:205], 0, s[8:9]
	s_mov_b32 m0, s54
	ds_read_b128 v[162:165], v210 offset:49152
	ds_read_b128 v[166:169], v210 offset:50176
	ds_read_b128 v[170:173], v210 offset:51200
	ds_read_b128 v[174:177], v210 offset:52224
	ds_read_b128 v[200:203], v210 offset:53248
	ds_read_b128 v[212:215], v210 offset:54272
	ds_read_b128 v[216:219], v210 offset:55296
	ds_read_b128 v[224:227], v210 offset:56320
	global_load_lds_dwordx4 v[204:205], off
	s_add_i32 m0, s54, 0x2000
	s_add_u32 s52, s52, 0x100080
	v_lshl_add_u64 v[204:205], v[220:221], 0, s[8:9]
	s_addc_u32 s53, s53, 0
	s_add_i32 s54, s91, s31
	global_load_lds_dwordx4 v[204:205], off
	v_lshl_add_u64 v[204:205], s[52:53], 0, v[182:183]
	s_mov_b32 m0, s54
	s_nop 0
	global_load_lds_dwordx4 v[204:205], off
	v_lshl_add_u64 v[204:205], s[52:53], 0, v[178:179]
	s_add_i32 m0, s54, 0x2000
	s_nop 0
	global_load_lds_dwordx4 v[204:205], off
	v_lshl_add_u64 v[204:205], v[228:229], 0, s[8:9]
	s_mov_b32 m0, s62
	s_nop 0
	global_load_lds_dwordx4 v[204:205], off
	v_lshl_add_u64 v[204:205], v[230:231], 0, s[8:9]
	s_mov_b32 m0, s63
	s_nop 0
	global_load_lds_dwordx4 v[204:205], off
	s_waitcnt vmcnt(8)
	s_waitcnt lgkmcnt(0)
	s_barrier
	v_mfma_f32_16x16x32_bf16 v[62:65], v[130:133], v[162:165], v[62:65]
	v_mfma_f32_16x16x32_bf16 v[58:61], v[138:141], v[162:165], v[58:61]
	v_mfma_f32_16x16x32_bf16 v[50:53], v[130:133], v[170:173], v[50:53]
	v_mfma_f32_16x16x32_bf16 v[42:45], v[138:141], v[170:173], v[42:45]
	v_mfma_f32_16x16x32_bf16 v[34:37], v[130:133], v[200:203], v[34:37]
	v_mfma_f32_16x16x32_bf16 v[26:29], v[138:141], v[200:203], v[26:29]
	v_mfma_f32_16x16x32_bf16 v[18:21], v[130:133], v[216:219], v[18:21]
	v_mfma_f32_16x16x32_bf16 v[10:13], v[138:141], v[216:219], v[10:13]
	v_mfma_f32_16x16x32_bf16 v[62:65], v[134:137], v[166:169], v[62:65]
	v_mfma_f32_16x16x32_bf16 v[58:61], v[142:145], v[166:169], v[58:61]
	v_mfma_f32_16x16x32_bf16 v[50:53], v[134:137], v[174:177], v[50:53]
	v_mfma_f32_16x16x32_bf16 v[42:45], v[142:145], v[174:177], v[42:45]
	v_mfma_f32_16x16x32_bf16 v[34:37], v[134:137], v[212:215], v[34:37]
	v_mfma_f32_16x16x32_bf16 v[26:29], v[142:145], v[212:215], v[26:29]
	v_mfma_f32_16x16x32_bf16 v[18:21], v[134:137], v[224:227], v[18:21]
	v_mfma_f32_16x16x32_bf16 v[10:13], v[142:145], v[224:227], v[10:13]
	v_mfma_f32_16x16x32_bf16 v[54:57], v[146:149], v[162:165], v[54:57]
	v_mfma_f32_16x16x32_bf16 v[46:49], v[154:157], v[162:165], v[46:49]
	v_mfma_f32_16x16x32_bf16 v[38:41], v[146:149], v[170:173], v[38:41]
	v_mfma_f32_16x16x32_bf16 v[30:33], v[154:157], v[170:173], v[30:33]
	v_mfma_f32_16x16x32_bf16 v[22:25], v[146:149], v[200:203], v[22:25]
	v_mfma_f32_16x16x32_bf16 v[14:17], v[154:157], v[200:203], v[14:17]
	v_mfma_f32_16x16x32_bf16 v[6:9], v[146:149], v[216:219], v[6:9]
	v_mfma_f32_16x16x32_bf16 v[2:5], v[154:157], v[216:219], v[2:5]
	v_mfma_f32_16x16x32_bf16 v[54:57], v[150:153], v[166:169], v[54:57]
	v_mfma_f32_16x16x32_bf16 v[46:49], v[158:161], v[166:169], v[46:49]
	v_mfma_f32_16x16x32_bf16 v[38:41], v[150:153], v[174:177], v[38:41]
	v_mfma_f32_16x16x32_bf16 v[30:33], v[158:161], v[174:177], v[30:33]
	v_mfma_f32_16x16x32_bf16 v[22:25], v[150:153], v[212:215], v[22:25]
	v_mfma_f32_16x16x32_bf16 v[14:17], v[158:161], v[212:215], v[14:17]
	v_mfma_f32_16x16x32_bf16 v[6:9], v[150:153], v[224:227], v[6:9]
	v_mfma_f32_16x16x32_bf16 v[2:5], v[158:161], v[224:227], v[2:5]
	s_barrier
	s_add_i32 s89, s89, 2
	s_add_u32 s50, s50, 0x100
	s_addc_u32 s51, s51, 0
	s_add_u32 s87, s87, 0x100
	s_addc_u32 s88, s88, 0
.LBB0_224:
	ds_read_b128 v[130:133], v208
	ds_read_b128 v[134:137], v208 offset:1024
	ds_read_b128 v[138:141], v208 offset:2048
	ds_read_b128 v[142:145], v208 offset:3072
	ds_read_b128 v[146:149], v209
	ds_read_b128 v[150:153], v209 offset:1024
	ds_read_b128 v[154:157], v209 offset:2048
	ds_read_b128 v[158:161], v209 offset:3072
	s_add_u32 s52, s50, 0xfff00080
	s_addc_u32 s53, s51, -1
	s_cmp_eq_u32 s89, 60
	s_cselect_b32 s55, s43, s53
	s_cselect_b32 s54, s85, s52
	s_cselect_b32 s53, s41, s88
	s_cselect_b32 s52, s86, s87
	v_lshl_add_u64 v[204:205], s[50:51], 0, v[192:193]
	s_add_i32 m0, s56, 0xc000
	ds_read_b128 v[162:165], v210
	ds_read_b128 v[166:169], v210 offset:1024
	ds_read_b128 v[170:173], v210 offset:2048
	ds_read_b128 v[174:177], v210 offset:3072
	ds_read_b128 v[200:203], v210 offset:4096
	ds_read_b128 v[212:215], v210 offset:5120
	ds_read_b128 v[216:219], v210 offset:6144
	ds_read_b128 v[224:227], v210 offset:7168
	global_load_lds_dwordx4 v[204:205], off
	v_lshl_add_u64 v[204:205], s[50:51], 0, v[194:195]
	s_add_i32 m0, s56, 0xe000
	s_nop 0
	global_load_lds_dwordx4 v[204:205], off
	s_waitcnt vmcnt(8)
	s_waitcnt lgkmcnt(0)
	s_barrier
	v_mfma_f32_16x16x32_bf16 v[126:129], v[130:133], v[162:165], v[126:129]
	v_mfma_f32_16x16x32_bf16 v[122:125], v[138:141], v[162:165], v[122:125]
	v_mfma_f32_16x16x32_bf16 v[110:113], v[130:133], v[170:173], v[110:113]
	v_mfma_f32_16x16x32_bf16 v[106:109], v[138:141], v[170:173], v[106:109]
	v_mfma_f32_16x16x32_bf16 v[94:97], v[130:133], v[200:203], v[94:97]
	v_mfma_f32_16x16x32_bf16 v[90:93], v[138:141], v[200:203], v[90:93]
	v_mfma_f32_16x16x32_bf16 v[78:81], v[130:133], v[216:219], v[78:81]
	v_mfma_f32_16x16x32_bf16 v[74:77], v[138:141], v[216:219], v[74:77]
	v_mfma_f32_16x16x32_bf16 v[126:129], v[134:137], v[166:169], v[126:129]
	v_mfma_f32_16x16x32_bf16 v[122:125], v[142:145], v[166:169], v[122:125]
	v_mfma_f32_16x16x32_bf16 v[110:113], v[134:137], v[174:177], v[110:113]
	v_mfma_f32_16x16x32_bf16 v[106:109], v[142:145], v[174:177], v[106:109]
	v_mfma_f32_16x16x32_bf16 v[94:97], v[134:137], v[212:215], v[94:97]
	v_mfma_f32_16x16x32_bf16 v[90:93], v[142:145], v[212:215], v[90:93]
	v_mfma_f32_16x16x32_bf16 v[78:81], v[134:137], v[224:227], v[78:81]
	v_mfma_f32_16x16x32_bf16 v[74:77], v[142:145], v[224:227], v[74:77]
	v_mfma_f32_16x16x32_bf16 v[118:121], v[146:149], v[162:165], v[118:121]
	v_mfma_f32_16x16x32_bf16 v[114:117], v[154:157], v[162:165], v[114:117]
	v_mfma_f32_16x16x32_bf16 v[102:105], v[146:149], v[170:173], v[102:105]
	v_mfma_f32_16x16x32_bf16 v[98:101], v[154:157], v[170:173], v[98:101]
	v_mfma_f32_16x16x32_bf16 v[86:89], v[146:149], v[200:203], v[86:89]
	v_mfma_f32_16x16x32_bf16 v[82:85], v[154:157], v[200:203], v[82:85]
	v_mfma_f32_16x16x32_bf16 v[70:73], v[146:149], v[216:219], v[70:73]
	v_mfma_f32_16x16x32_bf16 v[66:69], v[154:157], v[216:219], v[66:69]
	v_mfma_f32_16x16x32_bf16 v[118:121], v[150:153], v[166:169], v[118:121]
	v_mfma_f32_16x16x32_bf16 v[114:117], v[158:161], v[166:169], v[114:117]
	v_mfma_f32_16x16x32_bf16 v[102:105], v[150:153], v[174:177], v[102:105]
	v_mfma_f32_16x16x32_bf16 v[98:101], v[158:161], v[174:177], v[98:101]
	v_mfma_f32_16x16x32_bf16 v[86:89], v[150:153], v[212:215], v[86:89]
	v_mfma_f32_16x16x32_bf16 v[82:85], v[158:161], v[212:215], v[82:85]
	v_mfma_f32_16x16x32_bf16 v[70:73], v[150:153], v[224:227], v[70:73]
	v_mfma_f32_16x16x32_bf16 v[66:69], v[158:161], v[224:227], v[66:69]
	s_barrier
	s_add_i32 s90, s65, s31
	v_lshl_add_u64 v[204:205], s[52:53], 0, v[182:183]
	s_mov_b32 m0, s90
	ds_read_b128 v[162:165], v210 offset:16384
	ds_read_b128 v[166:169], v210 offset:17408
	ds_read_b128 v[170:173], v210 offset:18432
	ds_read_b128 v[174:177], v210 offset:19456
	ds_read_b128 v[200:203], v210 offset:20480
	ds_read_b128 v[212:215], v210 offset:21504
	ds_read_b128 v[216:219], v210 offset:22528
	ds_read_b128 v[224:227], v210 offset:23552
	global_load_lds_dwordx4 v[204:205], off
	s_add_i32 m0, s90, 0x2000
	s_add_u32 s90, s52, 0x100000
	v_lshl_add_u64 v[220:221], s[52:53], 0, v[178:179]
	s_addc_u32 s91, s53, 0
	s_add_i32 s92, s66, s31
	global_load_lds_dwordx4 v[220:221], off
	v_lshl_add_u64 v[228:229], s[90:91], 0, v[182:183]
	s_mov_b32 m0, s92
	v_lshl_add_u64 v[230:231], s[54:55], 0, v[180:181]
	global_load_lds_dwordx4 v[228:229], off
	v_lshl_add_u64 v[228:229], s[90:91], 0, v[178:179]
	s_add_i32 m0, s92, 0x2000
	s_nop 0
	global_load_lds_dwordx4 v[228:229], off
	v_lshl_add_u64 v[228:229], s[54:55], 0, v[184:185]
	s_mov_b32 m0, s56
	s_nop 0
	global_load_lds_dwordx4 v[228:229], off
	s_mov_b32 m0, s57
	s_nop 0
	global_load_lds_dwordx4 v[230:231], off
	s_waitcnt vmcnt(8)
	s_waitcnt lgkmcnt(0)
	s_barrier
	v_mfma_f32_16x16x32_bf16 v[62:65], v[130:133], v[162:165], v[62:65]
	v_mfma_f32_16x16x32_bf16 v[58:61], v[138:141], v[162:165], v[58:61]
	v_mfma_f32_16x16x32_bf16 v[50:53], v[130:133], v[170:173], v[50:53]
	v_mfma_f32_16x16x32_bf16 v[42:45], v[138:141], v[170:173], v[42:45]
	v_mfma_f32_16x16x32_bf16 v[34:37], v[130:133], v[200:203], v[34:37]
	v_mfma_f32_16x16x32_bf16 v[26:29], v[138:141], v[200:203], v[26:29]
	v_mfma_f32_16x16x32_bf16 v[18:21], v[130:133], v[216:219], v[18:21]
	v_mfma_f32_16x16x32_bf16 v[10:13], v[138:141], v[216:219], v[10:13]
	v_mfma_f32_16x16x32_bf16 v[62:65], v[134:137], v[166:169], v[62:65]
	v_mfma_f32_16x16x32_bf16 v[58:61], v[142:145], v[166:169], v[58:61]
	v_mfma_f32_16x16x32_bf16 v[50:53], v[134:137], v[174:177], v[50:53]
	v_mfma_f32_16x16x32_bf16 v[42:45], v[142:145], v[174:177], v[42:45]
	v_mfma_f32_16x16x32_bf16 v[34:37], v[134:137], v[212:215], v[34:37]
	v_mfma_f32_16x16x32_bf16 v[26:29], v[142:145], v[212:215], v[26:29]
	v_mfma_f32_16x16x32_bf16 v[18:21], v[134:137], v[224:227], v[18:21]
	v_mfma_f32_16x16x32_bf16 v[10:13], v[142:145], v[224:227], v[10:13]
	v_mfma_f32_16x16x32_bf16 v[54:57], v[146:149], v[162:165], v[54:57]
	v_mfma_f32_16x16x32_bf16 v[46:49], v[154:157], v[162:165], v[46:49]
	v_mfma_f32_16x16x32_bf16 v[38:41], v[146:149], v[170:173], v[38:41]
	v_mfma_f32_16x16x32_bf16 v[30:33], v[154:157], v[170:173], v[30:33]
	v_mfma_f32_16x16x32_bf16 v[22:25], v[146:149], v[200:203], v[22:25]
	v_mfma_f32_16x16x32_bf16 v[14:17], v[154:157], v[200:203], v[14:17]
	v_mfma_f32_16x16x32_bf16 v[6:9], v[146:149], v[216:219], v[6:9]
	v_mfma_f32_16x16x32_bf16 v[2:5], v[154:157], v[216:219], v[2:5]
	v_mfma_f32_16x16x32_bf16 v[54:57], v[150:153], v[166:169], v[54:57]
	v_mfma_f32_16x16x32_bf16 v[46:49], v[158:161], v[166:169], v[46:49]
	v_mfma_f32_16x16x32_bf16 v[38:41], v[150:153], v[174:177], v[38:41]
	v_mfma_f32_16x16x32_bf16 v[30:33], v[158:161], v[174:177], v[30:33]
	v_mfma_f32_16x16x32_bf16 v[22:25], v[150:153], v[212:215], v[22:25]
	v_mfma_f32_16x16x32_bf16 v[14:17], v[158:161], v[212:215], v[14:17]
	v_mfma_f32_16x16x32_bf16 v[6:9], v[150:153], v[224:227], v[6:9]
	v_mfma_f32_16x16x32_bf16 v[2:5], v[158:161], v[224:227], v[2:5]
	s_barrier
	s_add_i32 s90, 0, 0x18000
	s_add_i32 s91, 0, 0x1c000
	v_add_u32_e32 v142, s90, v189
	v_add_u32_e32 v158, s91, v189
	ds_read_b128 v[130:133], v142
	ds_read_b128 v[134:137], v142 offset:1024
	ds_read_b128 v[138:141], v142 offset:2048
	ds_read_b128 v[142:145], v142 offset:3072
	ds_read_b128 v[146:149], v158
	ds_read_b128 v[150:153], v158 offset:1024
	ds_read_b128 v[154:157], v158 offset:2048
	ds_read_b128 v[158:161], v158 offset:3072
	s_add_u32 s54, s54, 0x100000
	s_addc_u32 s55, s55, 0
	s_mov_b32 m0, s58
	v_lshl_add_u64 v[232:233], s[54:55], 0, v[184:185]
	ds_read_b128 v[162:165], v210 offset:32768
	ds_read_b128 v[166:169], v210 offset:33792
	ds_read_b128 v[170:173], v210 offset:34816
	ds_read_b128 v[174:177], v210 offset:35840
	ds_read_b128 v[200:203], v210 offset:36864
	ds_read_b128 v[212:215], v210 offset:37888
	ds_read_b128 v[216:219], v210 offset:38912
	ds_read_b128 v[224:227], v210 offset:39936
	global_load_lds_dwordx4 v[232:233], off
	v_lshl_add_u64 v[232:233], s[54:55], 0, v[180:181]
	s_mov_b32 m0, s59
	s_nop 0
	global_load_lds_dwordx4 v[232:233], off
	s_waitcnt vmcnt(8)
	s_waitcnt lgkmcnt(0)
	s_barrier
	v_mfma_f32_16x16x32_bf16 v[126:129], v[130:133], v[162:165], v[126:129]
	v_mfma_f32_16x16x32_bf16 v[122:125], v[138:141], v[162:165], v[122:125]
	v_mfma_f32_16x16x32_bf16 v[110:113], v[130:133], v[170:173], v[110:113]
	v_mfma_f32_16x16x32_bf16 v[106:109], v[138:141], v[170:173], v[106:109]
	v_mfma_f32_16x16x32_bf16 v[94:97], v[130:133], v[200:203], v[94:97]
	v_mfma_f32_16x16x32_bf16 v[90:93], v[138:141], v[200:203], v[90:93]
	v_mfma_f32_16x16x32_bf16 v[78:81], v[130:133], v[216:219], v[78:81]
	v_mfma_f32_16x16x32_bf16 v[74:77], v[138:141], v[216:219], v[74:77]
	v_mfma_f32_16x16x32_bf16 v[126:129], v[134:137], v[166:169], v[126:129]
	v_mfma_f32_16x16x32_bf16 v[122:125], v[142:145], v[166:169], v[122:125]
	v_mfma_f32_16x16x32_bf16 v[110:113], v[134:137], v[174:177], v[110:113]
	v_mfma_f32_16x16x32_bf16 v[106:109], v[142:145], v[174:177], v[106:109]
	v_mfma_f32_16x16x32_bf16 v[94:97], v[134:137], v[212:215], v[94:97]
	v_mfma_f32_16x16x32_bf16 v[90:93], v[142:145], v[212:215], v[90:93]
	v_mfma_f32_16x16x32_bf16 v[78:81], v[134:137], v[224:227], v[78:81]
	v_mfma_f32_16x16x32_bf16 v[74:77], v[142:145], v[224:227], v[74:77]
	v_mfma_f32_16x16x32_bf16 v[118:121], v[146:149], v[162:165], v[118:121]
	v_mfma_f32_16x16x32_bf16 v[114:117], v[154:157], v[162:165], v[114:117]
	v_mfma_f32_16x16x32_bf16 v[102:105], v[146:149], v[170:173], v[102:105]
	v_mfma_f32_16x16x32_bf16 v[98:101], v[154:157], v[170:173], v[98:101]
	v_mfma_f32_16x16x32_bf16 v[86:89], v[146:149], v[200:203], v[86:89]
	v_mfma_f32_16x16x32_bf16 v[82:85], v[154:157], v[200:203], v[82:85]
	v_mfma_f32_16x16x32_bf16 v[70:73], v[146:149], v[216:219], v[70:73]
	v_mfma_f32_16x16x32_bf16 v[66:69], v[154:157], v[216:219], v[66:69]
	v_mfma_f32_16x16x32_bf16 v[118:121], v[150:153], v[166:169], v[118:121]
	v_mfma_f32_16x16x32_bf16 v[114:117], v[158:161], v[166:169], v[114:117]
	v_mfma_f32_16x16x32_bf16 v[102:105], v[150:153], v[174:177], v[102:105]
	v_mfma_f32_16x16x32_bf16 v[98:101], v[158:161], v[174:177], v[98:101]
	v_mfma_f32_16x16x32_bf16 v[86:89], v[150:153], v[212:215], v[86:89]
	v_mfma_f32_16x16x32_bf16 v[82:85], v[158:161], v[212:215], v[82:85]
	v_mfma_f32_16x16x32_bf16 v[70:73], v[150:153], v[224:227], v[70:73]
	v_mfma_f32_16x16x32_bf16 v[66:69], v[158:161], v[224:227], v[66:69]
	s_barrier
	s_add_i32 s54, s90, s31
	v_lshl_add_u64 v[204:205], v[204:205], 0, s[8:9]
	s_mov_b32 m0, s54
	ds_read_b128 v[162:165], v210 offset:49152
	ds_read_b128 v[166:169], v210 offset:50176
	ds_read_b128 v[170:173], v210 offset:51200
	ds_read_b128 v[174:177], v210 offset:52224
	ds_read_b128 v[200:203], v210 offset:53248
	ds_read_b128 v[212:215], v210 offset:54272
	ds_read_b128 v[216:219], v210 offset:55296
	ds_read_b128 v[224:227], v210 offset:56320
	global_load_lds_dwordx4 v[204:205], off
	s_add_i32 m0, s54, 0x2000
	s_add_u32 s52, s52, 0x100080
	v_lshl_add_u64 v[204:205], v[220:221], 0, s[8:9]
	s_addc_u32 s53, s53, 0
	s_add_i32 s54, s91, s31
	global_load_lds_dwordx4 v[204:205], off
	v_lshl_add_u64 v[204:205], s[52:53], 0, v[182:183]
	s_mov_b32 m0, s54
	s_nop 0
	global_load_lds_dwordx4 v[204:205], off
	v_lshl_add_u64 v[204:205], s[52:53], 0, v[178:179]
	s_add_i32 m0, s54, 0x2000
	s_nop 0
	global_load_lds_dwordx4 v[204:205], off
	v_lshl_add_u64 v[204:205], v[228:229], 0, s[8:9]
	s_mov_b32 m0, s62
	s_nop 0
	global_load_lds_dwordx4 v[204:205], off
	v_lshl_add_u64 v[204:205], v[230:231], 0, s[8:9]
	s_mov_b32 m0, s63
	s_nop 0
	global_load_lds_dwordx4 v[204:205], off
	s_waitcnt vmcnt(8)
	s_waitcnt lgkmcnt(0)
	s_barrier
	v_mfma_f32_16x16x32_bf16 v[62:65], v[130:133], v[162:165], v[62:65]
	v_mfma_f32_16x16x32_bf16 v[58:61], v[138:141], v[162:165], v[58:61]
	v_mfma_f32_16x16x32_bf16 v[50:53], v[130:133], v[170:173], v[50:53]
	v_mfma_f32_16x16x32_bf16 v[42:45], v[138:141], v[170:173], v[42:45]
	v_mfma_f32_16x16x32_bf16 v[34:37], v[130:133], v[200:203], v[34:37]
	v_mfma_f32_16x16x32_bf16 v[26:29], v[138:141], v[200:203], v[26:29]
	v_mfma_f32_16x16x32_bf16 v[18:21], v[130:133], v[216:219], v[18:21]
	v_mfma_f32_16x16x32_bf16 v[10:13], v[138:141], v[216:219], v[10:13]
	v_mfma_f32_16x16x32_bf16 v[62:65], v[134:137], v[166:169], v[62:65]
	v_mfma_f32_16x16x32_bf16 v[58:61], v[142:145], v[166:169], v[58:61]
	v_mfma_f32_16x16x32_bf16 v[50:53], v[134:137], v[174:177], v[50:53]
	v_mfma_f32_16x16x32_bf16 v[42:45], v[142:145], v[174:177], v[42:45]
	v_mfma_f32_16x16x32_bf16 v[34:37], v[134:137], v[212:215], v[34:37]
	v_mfma_f32_16x16x32_bf16 v[26:29], v[142:145], v[212:215], v[26:29]
	v_mfma_f32_16x16x32_bf16 v[18:21], v[134:137], v[224:227], v[18:21]
	v_mfma_f32_16x16x32_bf16 v[10:13], v[142:145], v[224:227], v[10:13]
	v_mfma_f32_16x16x32_bf16 v[54:57], v[146:149], v[162:165], v[54:57]
	v_mfma_f32_16x16x32_bf16 v[46:49], v[154:157], v[162:165], v[46:49]
	v_mfma_f32_16x16x32_bf16 v[38:41], v[146:149], v[170:173], v[38:41]
	v_mfma_f32_16x16x32_bf16 v[30:33], v[154:157], v[170:173], v[30:33]
	v_mfma_f32_16x16x32_bf16 v[22:25], v[146:149], v[200:203], v[22:25]
	v_mfma_f32_16x16x32_bf16 v[14:17], v[154:157], v[200:203], v[14:17]
	v_mfma_f32_16x16x32_bf16 v[6:9], v[146:149], v[216:219], v[6:9]
	v_mfma_f32_16x16x32_bf16 v[2:5], v[154:157], v[216:219], v[2:5]
	v_mfma_f32_16x16x32_bf16 v[54:57], v[150:153], v[166:169], v[54:57]
	v_mfma_f32_16x16x32_bf16 v[46:49], v[158:161], v[166:169], v[46:49]
	v_mfma_f32_16x16x32_bf16 v[38:41], v[150:153], v[174:177], v[38:41]
	v_mfma_f32_16x16x32_bf16 v[30:33], v[158:161], v[174:177], v[30:33]
	v_mfma_f32_16x16x32_bf16 v[22:25], v[150:153], v[212:215], v[22:25]
	v_mfma_f32_16x16x32_bf16 v[14:17], v[158:161], v[212:215], v[14:17]
	v_mfma_f32_16x16x32_bf16 v[6:9], v[150:153], v[224:227], v[6:9]
	v_mfma_f32_16x16x32_bf16 v[2:5], v[158:161], v[224:227], v[2:5]
	s_barrier
	s_add_i32 s89, s89, 2
	s_add_u32 s50, s50, 0x100
	s_addc_u32 s51, s51, 0
	s_add_u32 s87, s87, 0x100
	s_addc_u32 s88, s88, 0
	s_cmp_gt_u32 s89, 61
	s_cbranch_scc0 .LBB0_224
	s_and_b64 vcc, exec, s[10:11]
	s_cbranch_vccz .LBB0_229
	s_barrier
	v_lshl_add_u32 v200, s0, 8, v1
	s_cmp_gt_i32 s84, 15
	s_mov_b64 s[50:51], -1
	s_cbranch_scc1 .LBB0_230

.Lpeelb:
	v_add_u32_e32 v142, s51, v220
	v_add_u32_e32 v158, s81, v220
	ds_read_b128 v[130:133], v142
	ds_read_b128 v[134:137], v142 offset:1024
	ds_read_b128 v[138:141], v142 offset:2048
	ds_read_b128 v[142:145], v142 offset:3072
	ds_read_b128 v[146:149], v158
	ds_read_b128 v[150:153], v158 offset:1024
	ds_read_b128 v[154:157], v158 offset:2048
	ds_read_b128 v[158:161], v158 offset:3072
	s_add_u32 s16, s0, 0xfff00080
	s_addc_u32 s17, s1, -1
	s_cmp_eq_u32 s26, 60
	s_cselect_b32 s19, s20, s17
	s_cselect_b32 s18, s21, s16
	s_cselect_b32 s17, s22, s25
	s_cselect_b32 s16, s23, s24
	v_lshl_add_u64 v[218:219], s[0:1], 0, v[194:195]
	s_add_i32 m0, s31, 0xc000
	ds_read_b128 v[162:165], v233
	ds_read_b128 v[166:169], v233 offset:1024
	ds_read_b128 v[170:173], v233 offset:2048
	ds_read_b128 v[174:177], v233 offset:3072
	ds_read_b128 v[202:205], v233 offset:4096
	ds_read_b128 v[206:209], v233 offset:5120
	ds_read_b128 v[210:213], v233 offset:6144
	ds_read_b128 v[214:217], v233 offset:7168
	global_load_lds_dwordx4 v[218:219], off
	v_lshl_add_u64 v[218:219], s[0:1], 0, v[196:197]
	s_add_i32 m0, s31, 0xe000
	s_nop 0
	global_load_lds_dwordx4 v[218:219], off
	s_waitcnt vmcnt(8)
	s_waitcnt lgkmcnt(0)
	s_barrier
	v_mfma_f32_16x16x32_bf16 v[90:93], v[130:133], v[162:165], 0
	v_mfma_f32_16x16x32_bf16 v[58:61], v[138:141], v[162:165], 0
	v_mfma_f32_16x16x32_bf16 v[98:101], v[130:133], v[170:173], 0
	v_mfma_f32_16x16x32_bf16 v[66:69], v[138:141], v[170:173], 0
	v_mfma_f32_16x16x32_bf16 v[102:105], v[130:133], v[202:205], 0
	v_mfma_f32_16x16x32_bf16 v[70:73], v[138:141], v[202:205], 0
	v_mfma_f32_16x16x32_bf16 v[110:113], v[130:133], v[210:213], 0
	v_mfma_f32_16x16x32_bf16 v[78:81], v[138:141], v[210:213], 0
	v_mfma_f32_16x16x32_bf16 v[90:93], v[134:137], v[166:169], v[90:93]
	v_mfma_f32_16x16x32_bf16 v[58:61], v[142:145], v[166:169], v[58:61]
	v_mfma_f32_16x16x32_bf16 v[98:101], v[134:137], v[174:177], v[98:101]
	v_mfma_f32_16x16x32_bf16 v[66:69], v[142:145], v[174:177], v[66:69]
	v_mfma_f32_16x16x32_bf16 v[102:105], v[134:137], v[206:209], v[102:105]
	v_mfma_f32_16x16x32_bf16 v[70:73], v[142:145], v[206:209], v[70:73]
	v_mfma_f32_16x16x32_bf16 v[110:113], v[134:137], v[214:217], v[110:113]
	v_mfma_f32_16x16x32_bf16 v[78:81], v[142:145], v[214:217], v[78:81]
	v_mfma_f32_16x16x32_bf16 v[26:29], v[146:149], v[162:165], 0
	v_mfma_f32_16x16x32_bf16 v[2:5], v[154:157], v[162:165], 0
	v_mfma_f32_16x16x32_bf16 v[34:37], v[146:149], v[170:173], 0
	v_mfma_f32_16x16x32_bf16 v[6:9], v[154:157], v[170:173], 0
	v_mfma_f32_16x16x32_bf16 v[38:41], v[146:149], v[202:205], 0
	v_mfma_f32_16x16x32_bf16 v[10:13], v[154:157], v[202:205], 0
	v_mfma_f32_16x16x32_bf16 v[46:49], v[146:149], v[210:213], 0
	v_mfma_f32_16x16x32_bf16 v[14:17], v[154:157], v[210:213], 0
	v_mfma_f32_16x16x32_bf16 v[26:29], v[150:153], v[166:169], v[26:29]
	v_mfma_f32_16x16x32_bf16 v[2:5], v[158:161], v[166:169], v[2:5]
	v_mfma_f32_16x16x32_bf16 v[34:37], v[150:153], v[174:177], v[34:37]
	v_mfma_f32_16x16x32_bf16 v[6:9], v[158:161], v[174:177], v[6:9]
	v_mfma_f32_16x16x32_bf16 v[38:41], v[150:153], v[206:209], v[38:41]
	v_mfma_f32_16x16x32_bf16 v[10:13], v[158:161], v[206:209], v[10:13]
	v_mfma_f32_16x16x32_bf16 v[46:49], v[150:153], v[214:217], v[46:49]
	v_mfma_f32_16x16x32_bf16 v[14:17], v[158:161], v[214:217], v[14:17]
	s_barrier
	s_add_i32 s27, s51, s15
	v_lshl_add_u64 v[218:219], s[16:17], 0, v[178:179]
	s_mov_b32 m0, s27
	ds_read_b128 v[162:165], v233 offset:16384
	ds_read_b128 v[166:169], v233 offset:17408
	ds_read_b128 v[170:173], v233 offset:18432
	ds_read_b128 v[174:177], v233 offset:19456
	ds_read_b128 v[202:205], v233 offset:20480
	ds_read_b128 v[206:209], v233 offset:21504
	ds_read_b128 v[210:213], v233 offset:22528
	ds_read_b128 v[214:217], v233 offset:23552
	global_load_lds_dwordx4 v[218:219], off
	s_add_i32 m0, s27, 0x2000
	s_add_u32 s62, s16, 0x100000
	v_lshl_add_u64 v[242:243], s[16:17], 0, v[180:181]
	s_addc_u32 s63, s17, 0
	s_add_i32 s27, s81, s15
	global_load_lds_dwordx4 v[242:243], off
	v_lshl_add_u64 v[244:245], s[62:63], 0, v[178:179]
	s_mov_b32 m0, s27
	v_lshl_add_u64 v[246:247], s[18:19], 0, v[180:181]
	global_load_lds_dwordx4 v[244:245], off
	v_lshl_add_u64 v[244:245], s[62:63], 0, v[180:181]
	s_add_i32 m0, s27, 0x2000
	s_nop 0
	global_load_lds_dwordx4 v[244:245], off
	v_lshl_add_u64 v[244:245], s[18:19], 0, v[178:179]
	s_mov_b32 m0, s31
	s_nop 0
	global_load_lds_dwordx4 v[244:245], off
	s_mov_b32 m0, s34
	s_nop 0
	global_load_lds_dwordx4 v[246:247], off
	s_waitcnt vmcnt(8)
	s_waitcnt lgkmcnt(0)
	s_barrier
	v_mfma_f32_16x16x32_bf16 v[114:117], v[130:133], v[162:165], 0
	v_mfma_f32_16x16x32_bf16 v[82:85], v[138:141], v[162:165], 0
	v_mfma_f32_16x16x32_bf16 v[118:121], v[130:133], v[170:173], 0
	v_mfma_f32_16x16x32_bf16 v[86:89], v[138:141], v[170:173], 0
	v_mfma_f32_16x16x32_bf16 v[122:125], v[130:133], v[202:205], 0
	v_mfma_f32_16x16x32_bf16 v[94:97], v[138:141], v[202:205], 0
	v_mfma_f32_16x16x32_bf16 v[126:129], v[130:133], v[210:213], 0
	v_mfma_f32_16x16x32_bf16 v[106:109], v[138:141], v[210:213], 0
	v_mfma_f32_16x16x32_bf16 v[114:117], v[134:137], v[166:169], v[114:117]
	v_mfma_f32_16x16x32_bf16 v[82:85], v[142:145], v[166:169], v[82:85]
	v_mfma_f32_16x16x32_bf16 v[118:121], v[134:137], v[174:177], v[118:121]
	v_mfma_f32_16x16x32_bf16 v[86:89], v[142:145], v[174:177], v[86:89]
	v_mfma_f32_16x16x32_bf16 v[122:125], v[134:137], v[206:209], v[122:125]
	v_mfma_f32_16x16x32_bf16 v[94:97], v[142:145], v[206:209], v[94:97]
	v_mfma_f32_16x16x32_bf16 v[126:129], v[134:137], v[214:217], v[126:129]
	v_mfma_f32_16x16x32_bf16 v[106:109], v[142:145], v[214:217], v[106:109]
	v_mfma_f32_16x16x32_bf16 v[50:53], v[146:149], v[162:165], 0
	v_mfma_f32_16x16x32_bf16 v[18:21], v[154:157], v[162:165], 0
	v_mfma_f32_16x16x32_bf16 v[54:57], v[146:149], v[170:173], 0
	v_mfma_f32_16x16x32_bf16 v[22:25], v[154:157], v[170:173], 0
	v_mfma_f32_16x16x32_bf16 v[62:65], v[146:149], v[202:205], 0
	v_mfma_f32_16x16x32_bf16 v[30:33], v[154:157], v[202:205], 0
	v_mfma_f32_16x16x32_bf16 v[74:77], v[146:149], v[210:213], 0
	v_mfma_f32_16x16x32_bf16 v[42:45], v[154:157], v[210:213], 0
	v_mfma_f32_16x16x32_bf16 v[50:53], v[150:153], v[166:169], v[50:53]
	v_mfma_f32_16x16x32_bf16 v[18:21], v[158:161], v[166:169], v[18:21]
	v_mfma_f32_16x16x32_bf16 v[54:57], v[150:153], v[174:177], v[54:57]
	v_mfma_f32_16x16x32_bf16 v[22:25], v[158:161], v[174:177], v[22:25]
	v_mfma_f32_16x16x32_bf16 v[62:65], v[150:153], v[206:209], v[62:65]
	v_mfma_f32_16x16x32_bf16 v[30:33], v[158:161], v[206:209], v[30:33]
	v_mfma_f32_16x16x32_bf16 v[74:77], v[150:153], v[214:217], v[74:77]
	v_mfma_f32_16x16x32_bf16 v[42:45], v[158:161], v[214:217], v[42:45]
	s_barrier
	s_add_i32 s27, 0, 0x18000
	s_add_i32 s59, 0, 0x1c000
	v_add_u32_e32 v142, s27, v220
	v_add_u32_e32 v158, s59, v220
	ds_read_b128 v[130:133], v142
	ds_read_b128 v[134:137], v142 offset:1024
	ds_read_b128 v[138:141], v142 offset:2048
	ds_read_b128 v[142:145], v142 offset:3072
	ds_read_b128 v[146:149], v158
	ds_read_b128 v[150:153], v158 offset:1024
	ds_read_b128 v[154:157], v158 offset:2048
	ds_read_b128 v[158:161], v158 offset:3072
	s_add_u32 s18, s18, 0x100000
	s_addc_u32 s19, s19, 0
	s_mov_b32 m0, s35
	v_lshl_add_u64 v[248:249], s[18:19], 0, v[178:179]
	ds_read_b128 v[162:165], v233 offset:32768
	ds_read_b128 v[166:169], v233 offset:33792
	ds_read_b128 v[170:173], v233 offset:34816
	ds_read_b128 v[174:177], v233 offset:35840
	ds_read_b128 v[202:205], v233 offset:36864
	ds_read_b128 v[206:209], v233 offset:37888
	ds_read_b128 v[210:213], v233 offset:38912
	ds_read_b128 v[214:217], v233 offset:39936
	global_load_lds_dwordx4 v[248:249], off
	v_lshl_add_u64 v[248:249], s[18:19], 0, v[180:181]
	s_mov_b32 m0, s86
	s_nop 0
	global_load_lds_dwordx4 v[248:249], off
	s_waitcnt vmcnt(8)
	s_waitcnt lgkmcnt(0)
	s_barrier
	v_mfma_f32_16x16x32_bf16 v[90:93], v[130:133], v[162:165], v[90:93]
	v_mfma_f32_16x16x32_bf16 v[58:61], v[138:141], v[162:165], v[58:61]
	v_mfma_f32_16x16x32_bf16 v[98:101], v[130:133], v[170:173], v[98:101]
	v_mfma_f32_16x16x32_bf16 v[66:69], v[138:141], v[170:173], v[66:69]
	v_mfma_f32_16x16x32_bf16 v[102:105], v[130:133], v[202:205], v[102:105]
	v_mfma_f32_16x16x32_bf16 v[70:73], v[138:141], v[202:205], v[70:73]
	v_mfma_f32_16x16x32_bf16 v[110:113], v[130:133], v[210:213], v[110:113]
	v_mfma_f32_16x16x32_bf16 v[78:81], v[138:141], v[210:213], v[78:81]
	v_mfma_f32_16x16x32_bf16 v[90:93], v[134:137], v[166:169], v[90:93]
	v_mfma_f32_16x16x32_bf16 v[58:61], v[142:145], v[166:169], v[58:61]
	v_mfma_f32_16x16x32_bf16 v[98:101], v[134:137], v[174:177], v[98:101]
	v_mfma_f32_16x16x32_bf16 v[66:69], v[142:145], v[174:177], v[66:69]
	v_mfma_f32_16x16x32_bf16 v[102:105], v[134:137], v[206:209], v[102:105]
	v_mfma_f32_16x16x32_bf16 v[70:73], v[142:145], v[206:209], v[70:73]
	v_mfma_f32_16x16x32_bf16 v[110:113], v[134:137], v[214:217], v[110:113]
	v_mfma_f32_16x16x32_bf16 v[78:81], v[142:145], v[214:217], v[78:81]
	v_mfma_f32_16x16x32_bf16 v[26:29], v[146:149], v[162:165], v[26:29]
	v_mfma_f32_16x16x32_bf16 v[2:5], v[154:157], v[162:165], v[2:5]
	v_mfma_f32_16x16x32_bf16 v[34:37], v[146:149], v[170:173], v[34:37]
	v_mfma_f32_16x16x32_bf16 v[6:9], v[154:157], v[170:173], v[6:9]
	v_mfma_f32_16x16x32_bf16 v[38:41], v[146:149], v[202:205], v[38:41]
	v_mfma_f32_16x16x32_bf16 v[10:13], v[154:157], v[202:205], v[10:13]
	v_mfma_f32_16x16x32_bf16 v[46:49], v[146:149], v[210:213], v[46:49]
	v_mfma_f32_16x16x32_bf16 v[14:17], v[154:157], v[210:213], v[14:17]
	v_mfma_f32_16x16x32_bf16 v[26:29], v[150:153], v[166:169], v[26:29]
	v_mfma_f32_16x16x32_bf16 v[2:5], v[158:161], v[166:169], v[2:5]
	v_mfma_f32_16x16x32_bf16 v[34:37], v[150:153], v[174:177], v[34:37]
	v_mfma_f32_16x16x32_bf16 v[6:9], v[158:161], v[174:177], v[6:9]
	v_mfma_f32_16x16x32_bf16 v[38:41], v[150:153], v[206:209], v[38:41]
	v_mfma_f32_16x16x32_bf16 v[10:13], v[158:161], v[206:209], v[10:13]
	v_mfma_f32_16x16x32_bf16 v[46:49], v[150:153], v[214:217], v[46:49]
	v_mfma_f32_16x16x32_bf16 v[14:17], v[158:161], v[214:217], v[14:17]
	s_barrier
	s_add_i32 s18, s27, s15
	v_lshl_add_u64 v[218:219], v[218:219], 0, s[44:45]
	s_mov_b32 m0, s18
	ds_read_b128 v[162:165], v233 offset:49152
	ds_read_b128 v[166:169], v233 offset:50176
	ds_read_b128 v[170:173], v233 offset:51200
	ds_read_b128 v[174:177], v233 offset:52224
	ds_read_b128 v[202:205], v233 offset:53248
	ds_read_b128 v[206:209], v233 offset:54272
	ds_read_b128 v[210:213], v233 offset:55296
	ds_read_b128 v[214:217], v233 offset:56320
	global_load_lds_dwordx4 v[218:219], off
	s_add_i32 m0, s18, 0x2000
	s_add_u32 s16, s16, 0x100080
	v_lshl_add_u64 v[218:219], v[242:243], 0, s[44:45]
	s_addc_u32 s17, s17, 0
	s_add_i32 s18, s59, s15
	global_load_lds_dwordx4 v[218:219], off
	v_lshl_add_u64 v[218:219], s[16:17], 0, v[178:179]
	s_mov_b32 m0, s18
	s_nop 0
	global_load_lds_dwordx4 v[218:219], off
	v_lshl_add_u64 v[218:219], s[16:17], 0, v[180:181]
	s_add_i32 m0, s18, 0x2000
	s_nop 0
	global_load_lds_dwordx4 v[218:219], off
	v_lshl_add_u64 v[218:219], v[244:245], 0, s[44:45]
	s_mov_b32 m0, s66
	s_nop 0
	global_load_lds_dwordx4 v[218:219], off
	v_lshl_add_u64 v[218:219], v[246:247], 0, s[44:45]
	s_mov_b32 m0, s67
	s_nop 0
	global_load_lds_dwordx4 v[218:219], off
	s_waitcnt vmcnt(8)
	s_waitcnt lgkmcnt(0)
	s_barrier
	v_mfma_f32_16x16x32_bf16 v[114:117], v[130:133], v[162:165], v[114:117]
	v_mfma_f32_16x16x32_bf16 v[82:85], v[138:141], v[162:165], v[82:85]
	v_mfma_f32_16x16x32_bf16 v[118:121], v[130:133], v[170:173], v[118:121]
	v_mfma_f32_16x16x32_bf16 v[86:89], v[138:141], v[170:173], v[86:89]
	v_mfma_f32_16x16x32_bf16 v[122:125], v[130:133], v[202:205], v[122:125]
	v_mfma_f32_16x16x32_bf16 v[94:97], v[138:141], v[202:205], v[94:97]
	v_mfma_f32_16x16x32_bf16 v[126:129], v[130:133], v[210:213], v[126:129]
	v_mfma_f32_16x16x32_bf16 v[106:109], v[138:141], v[210:213], v[106:109]
	v_mfma_f32_16x16x32_bf16 v[114:117], v[134:137], v[166:169], v[114:117]
	v_mfma_f32_16x16x32_bf16 v[82:85], v[142:145], v[166:169], v[82:85]
	v_mfma_f32_16x16x32_bf16 v[118:121], v[134:137], v[174:177], v[118:121]
	v_mfma_f32_16x16x32_bf16 v[86:89], v[142:145], v[174:177], v[86:89]
	v_mfma_f32_16x16x32_bf16 v[122:125], v[134:137], v[206:209], v[122:125]
	v_mfma_f32_16x16x32_bf16 v[94:97], v[142:145], v[206:209], v[94:97]
	v_mfma_f32_16x16x32_bf16 v[126:129], v[134:137], v[214:217], v[126:129]
	v_mfma_f32_16x16x32_bf16 v[106:109], v[142:145], v[214:217], v[106:109]
	v_mfma_f32_16x16x32_bf16 v[50:53], v[146:149], v[162:165], v[50:53]
	v_mfma_f32_16x16x32_bf16 v[18:21], v[154:157], v[162:165], v[18:21]
	v_mfma_f32_16x16x32_bf16 v[54:57], v[146:149], v[170:173], v[54:57]
	v_mfma_f32_16x16x32_bf16 v[22:25], v[154:157], v[170:173], v[22:25]
	v_mfma_f32_16x16x32_bf16 v[62:65], v[146:149], v[202:205], v[62:65]
	v_mfma_f32_16x16x32_bf16 v[30:33], v[154:157], v[202:205], v[30:33]
	v_mfma_f32_16x16x32_bf16 v[74:77], v[146:149], v[210:213], v[74:77]
	v_mfma_f32_16x16x32_bf16 v[42:45], v[154:157], v[210:213], v[42:45]
	v_mfma_f32_16x16x32_bf16 v[50:53], v[150:153], v[166:169], v[50:53]
	v_mfma_f32_16x16x32_bf16 v[18:21], v[158:161], v[166:169], v[18:21]
	v_mfma_f32_16x16x32_bf16 v[54:57], v[150:153], v[174:177], v[54:57]
	v_mfma_f32_16x16x32_bf16 v[22:25], v[158:161], v[174:177], v[22:25]
	v_mfma_f32_16x16x32_bf16 v[62:65], v[150:153], v[206:209], v[62:65]
	v_mfma_f32_16x16x32_bf16 v[30:33], v[158:161], v[206:209], v[30:33]
	v_mfma_f32_16x16x32_bf16 v[74:77], v[150:153], v[214:217], v[74:77]
	v_mfma_f32_16x16x32_bf16 v[42:45], v[158:161], v[214:217], v[42:45]
	s_barrier
	s_add_i32 s26, s26, 2
	s_add_u32 s0, s0, 0x100
	s_addc_u32 s1, s1, 0
	s_add_u32 s24, s24, 0x100
	s_addc_u32 s25, s25, 0
.LBB0_672:
	v_add_u32_e32 v142, s51, v220
	v_add_u32_e32 v158, s81, v220
	ds_read_b128 v[130:133], v142
	ds_read_b128 v[134:137], v142 offset:1024
	ds_read_b128 v[138:141], v142 offset:2048
	ds_read_b128 v[142:145], v142 offset:3072
	ds_read_b128 v[146:149], v158
	ds_read_b128 v[150:153], v158 offset:1024
	ds_read_b128 v[154:157], v158 offset:2048
	ds_read_b128 v[158:161], v158 offset:3072
	s_add_u32 s16, s0, 0xfff00080
	s_addc_u32 s17, s1, -1
	s_cmp_eq_u32 s26, 60
	s_cselect_b32 s19, s20, s17
	s_cselect_b32 s18, s21, s16
	s_cselect_b32 s17, s22, s25
	s_cselect_b32 s16, s23, s24
	v_lshl_add_u64 v[218:219], s[0:1], 0, v[194:195]
	s_add_i32 m0, s31, 0xc000
	ds_read_b128 v[162:165], v233
	ds_read_b128 v[166:169], v233 offset:1024
	ds_read_b128 v[170:173], v233 offset:2048
	ds_read_b128 v[174:177], v233 offset:3072
	ds_read_b128 v[202:205], v233 offset:4096
	ds_read_b128 v[206:209], v233 offset:5120
	ds_read_b128 v[210:213], v233 offset:6144
	ds_read_b128 v[214:217], v233 offset:7168
	global_load_lds_dwordx4 v[218:219], off
	v_lshl_add_u64 v[218:219], s[0:1], 0, v[196:197]
	s_add_i32 m0, s31, 0xe000
	s_nop 0
	global_load_lds_dwordx4 v[218:219], off
	s_waitcnt vmcnt(8)
	s_waitcnt lgkmcnt(0)
	s_barrier
	v_mfma_f32_16x16x32_bf16 v[90:93], v[130:133], v[162:165], v[90:93]
	v_mfma_f32_16x16x32_bf16 v[58:61], v[138:141], v[162:165], v[58:61]
	v_mfma_f32_16x16x32_bf16 v[98:101], v[130:133], v[170:173], v[98:101]
	v_mfma_f32_16x16x32_bf16 v[66:69], v[138:141], v[170:173], v[66:69]
	v_mfma_f32_16x16x32_bf16 v[102:105], v[130:133], v[202:205], v[102:105]
	v_mfma_f32_16x16x32_bf16 v[70:73], v[138:141], v[202:205], v[70:73]
	v_mfma_f32_16x16x32_bf16 v[110:113], v[130:133], v[210:213], v[110:113]
	v_mfma_f32_16x16x32_bf16 v[78:81], v[138:141], v[210:213], v[78:81]
	v_mfma_f32_16x16x32_bf16 v[90:93], v[134:137], v[166:169], v[90:93]
	v_mfma_f32_16x16x32_bf16 v[58:61], v[142:145], v[166:169], v[58:61]
	v_mfma_f32_16x16x32_bf16 v[98:101], v[134:137], v[174:177], v[98:101]
	v_mfma_f32_16x16x32_bf16 v[66:69], v[142:145], v[174:177], v[66:69]
	v_mfma_f32_16x16x32_bf16 v[102:105], v[134:137], v[206:209], v[102:105]
	v_mfma_f32_16x16x32_bf16 v[70:73], v[142:145], v[206:209], v[70:73]
	v_mfma_f32_16x16x32_bf16 v[110:113], v[134:137], v[214:217], v[110:113]
	v_mfma_f32_16x16x32_bf16 v[78:81], v[142:145], v[214:217], v[78:81]
	v_mfma_f32_16x16x32_bf16 v[26:29], v[146:149], v[162:165], v[26:29]
	v_mfma_f32_16x16x32_bf16 v[2:5], v[154:157], v[162:165], v[2:5]
	v_mfma_f32_16x16x32_bf16 v[34:37], v[146:149], v[170:173], v[34:37]
	v_mfma_f32_16x16x32_bf16 v[6:9], v[154:157], v[170:173], v[6:9]
	v_mfma_f32_16x16x32_bf16 v[38:41], v[146:149], v[202:205], v[38:41]
	v_mfma_f32_16x16x32_bf16 v[10:13], v[154:157], v[202:205], v[10:13]
	v_mfma_f32_16x16x32_bf16 v[46:49], v[146:149], v[210:213], v[46:49]
	v_mfma_f32_16x16x32_bf16 v[14:17], v[154:157], v[210:213], v[14:17]
	v_mfma_f32_16x16x32_bf16 v[26:29], v[150:153], v[166:169], v[26:29]
	v_mfma_f32_16x16x32_bf16 v[2:5], v[158:161], v[166:169], v[2:5]
	v_mfma_f32_16x16x32_bf16 v[34:37], v[150:153], v[174:177], v[34:37]
	v_mfma_f32_16x16x32_bf16 v[6:9], v[158:161], v[174:177], v[6:9]
	v_mfma_f32_16x16x32_bf16 v[38:41], v[150:153], v[206:209], v[38:41]
	v_mfma_f32_16x16x32_bf16 v[10:13], v[158:161], v[206:209], v[10:13]
	v_mfma_f32_16x16x32_bf16 v[46:49], v[150:153], v[214:217], v[46:49]
	v_mfma_f32_16x16x32_bf16 v[14:17], v[158:161], v[214:217], v[14:17]
	s_barrier
	s_add_i32 s27, s51, s15
	v_lshl_add_u64 v[218:219], s[16:17], 0, v[178:179]
	s_mov_b32 m0, s27
	ds_read_b128 v[162:165], v233 offset:16384
	ds_read_b128 v[166:169], v233 offset:17408
	ds_read_b128 v[170:173], v233 offset:18432
	ds_read_b128 v[174:177], v233 offset:19456
	ds_read_b128 v[202:205], v233 offset:20480
	ds_read_b128 v[206:209], v233 offset:21504
	ds_read_b128 v[210:213], v233 offset:22528
	ds_read_b128 v[214:217], v233 offset:23552
	global_load_lds_dwordx4 v[218:219], off
	s_add_i32 m0, s27, 0x2000
	s_add_u32 s62, s16, 0x100000
	v_lshl_add_u64 v[242:243], s[16:17], 0, v[180:181]
	s_addc_u32 s63, s17, 0
	s_add_i32 s27, s81, s15
	global_load_lds_dwordx4 v[242:243], off
	v_lshl_add_u64 v[244:245], s[62:63], 0, v[178:179]
	s_mov_b32 m0, s27
	v_lshl_add_u64 v[246:247], s[18:19], 0, v[180:181]
	global_load_lds_dwordx4 v[244:245], off
	v_lshl_add_u64 v[244:245], s[62:63], 0, v[180:181]
	s_add_i32 m0, s27, 0x2000
	s_nop 0
	global_load_lds_dwordx4 v[244:245], off
	v_lshl_add_u64 v[244:245], s[18:19], 0, v[178:179]
	s_mov_b32 m0, s31
	s_nop 0
	global_load_lds_dwordx4 v[244:245], off
	s_mov_b32 m0, s34
	s_nop 0
	global_load_lds_dwordx4 v[246:247], off
	s_waitcnt vmcnt(8)
	s_waitcnt lgkmcnt(0)
	s_barrier
	v_mfma_f32_16x16x32_bf16 v[114:117], v[130:133], v[162:165], v[114:117]
	v_mfma_f32_16x16x32_bf16 v[82:85], v[138:141], v[162:165], v[82:85]
	v_mfma_f32_16x16x32_bf16 v[118:121], v[130:133], v[170:173], v[118:121]
	v_mfma_f32_16x16x32_bf16 v[86:89], v[138:141], v[170:173], v[86:89]
	v_mfma_f32_16x16x32_bf16 v[122:125], v[130:133], v[202:205], v[122:125]
	v_mfma_f32_16x16x32_bf16 v[94:97], v[138:141], v[202:205], v[94:97]
	v_mfma_f32_16x16x32_bf16 v[126:129], v[130:133], v[210:213], v[126:129]
	v_mfma_f32_16x16x32_bf16 v[106:109], v[138:141], v[210:213], v[106:109]
	v_mfma_f32_16x16x32_bf16 v[114:117], v[134:137], v[166:169], v[114:117]
	v_mfma_f32_16x16x32_bf16 v[82:85], v[142:145], v[166:169], v[82:85]
	v_mfma_f32_16x16x32_bf16 v[118:121], v[134:137], v[174:177], v[118:121]
	v_mfma_f32_16x16x32_bf16 v[86:89], v[142:145], v[174:177], v[86:89]
	v_mfma_f32_16x16x32_bf16 v[122:125], v[134:137], v[206:209], v[122:125]
	v_mfma_f32_16x16x32_bf16 v[94:97], v[142:145], v[206:209], v[94:97]
	v_mfma_f32_16x16x32_bf16 v[126:129], v[134:137], v[214:217], v[126:129]
	v_mfma_f32_16x16x32_bf16 v[106:109], v[142:145], v[214:217], v[106:109]
	v_mfma_f32_16x16x32_bf16 v[50:53], v[146:149], v[162:165], v[50:53]
	v_mfma_f32_16x16x32_bf16 v[18:21], v[154:157], v[162:165], v[18:21]
	v_mfma_f32_16x16x32_bf16 v[54:57], v[146:149], v[170:173], v[54:57]
	v_mfma_f32_16x16x32_bf16 v[22:25], v[154:157], v[170:173], v[22:25]
	v_mfma_f32_16x16x32_bf16 v[62:65], v[146:149], v[202:205], v[62:65]
	v_mfma_f32_16x16x32_bf16 v[30:33], v[154:157], v[202:205], v[30:33]
	v_mfma_f32_16x16x32_bf16 v[74:77], v[146:149], v[210:213], v[74:77]
	v_mfma_f32_16x16x32_bf16 v[42:45], v[154:157], v[210:213], v[42:45]
	v_mfma_f32_16x16x32_bf16 v[50:53], v[150:153], v[166:169], v[50:53]
	v_mfma_f32_16x16x32_bf16 v[18:21], v[158:161], v[166:169], v[18:21]
	v_mfma_f32_16x16x32_bf16 v[54:57], v[150:153], v[174:177], v[54:57]
	v_mfma_f32_16x16x32_bf16 v[22:25], v[158:161], v[174:177], v[22:25]
	v_mfma_f32_16x16x32_bf16 v[62:65], v[150:153], v[206:209], v[62:65]
	v_mfma_f32_16x16x32_bf16 v[30:33], v[158:161], v[206:209], v[30:33]
	v_mfma_f32_16x16x32_bf16 v[74:77], v[150:153], v[214:217], v[74:77]
	v_mfma_f32_16x16x32_bf16 v[42:45], v[158:161], v[214:217], v[42:45]
	s_barrier
	s_add_i32 s27, 0, 0x18000
	s_add_i32 s59, 0, 0x1c000
	v_add_u32_e32 v142, s27, v220
	v_add_u32_e32 v158, s59, v220
	ds_read_b128 v[130:133], v142
	ds_read_b128 v[134:137], v142 offset:1024
	ds_read_b128 v[138:141], v142 offset:2048
	ds_read_b128 v[142:145], v142 offset:3072
	ds_read_b128 v[146:149], v158
	ds_read_b128 v[150:153], v158 offset:1024
	ds_read_b128 v[154:157], v158 offset:2048
	ds_read_b128 v[158:161], v158 offset:3072
	s_add_u32 s18, s18, 0x100000
	s_addc_u32 s19, s19, 0
	s_mov_b32 m0, s35
	v_lshl_add_u64 v[248:249], s[18:19], 0, v[178:179]
	ds_read_b128 v[162:165], v233 offset:32768
	ds_read_b128 v[166:169], v233 offset:33792
	ds_read_b128 v[170:173], v233 offset:34816
	ds_read_b128 v[174:177], v233 offset:35840
	ds_read_b128 v[202:205], v233 offset:36864
	ds_read_b128 v[206:209], v233 offset:37888
	ds_read_b128 v[210:213], v233 offset:38912
	ds_read_b128 v[214:217], v233 offset:39936
	global_load_lds_dwordx4 v[248:249], off
	v_lshl_add_u64 v[248:249], s[18:19], 0, v[180:181]
	s_mov_b32 m0, s86
	s_nop 0
	global_load_lds_dwordx4 v[248:249], off
	s_waitcnt vmcnt(8)
	s_waitcnt lgkmcnt(0)
	s_barrier
	v_mfma_f32_16x16x32_bf16 v[90:93], v[130:133], v[162:165], v[90:93]
	v_mfma_f32_16x16x32_bf16 v[58:61], v[138:141], v[162:165], v[58:61]
	v_mfma_f32_16x16x32_bf16 v[98:101], v[130:133], v[170:173], v[98:101]
	v_mfma_f32_16x16x32_bf16 v[66:69], v[138:141], v[170:173], v[66:69]
	v_mfma_f32_16x16x32_bf16 v[102:105], v[130:133], v[202:205], v[102:105]
	v_mfma_f32_16x16x32_bf16 v[70:73], v[138:141], v[202:205], v[70:73]
	v_mfma_f32_16x16x32_bf16 v[110:113], v[130:133], v[210:213], v[110:113]
	v_mfma_f32_16x16x32_bf16 v[78:81], v[138:141], v[210:213], v[78:81]
	v_mfma_f32_16x16x32_bf16 v[90:93], v[134:137], v[166:169], v[90:93]
	v_mfma_f32_16x16x32_bf16 v[58:61], v[142:145], v[166:169], v[58:61]
	v_mfma_f32_16x16x32_bf16 v[98:101], v[134:137], v[174:177], v[98:101]
	v_mfma_f32_16x16x32_bf16 v[66:69], v[142:145], v[174:177], v[66:69]
	v_mfma_f32_16x16x32_bf16 v[102:105], v[134:137], v[206:209], v[102:105]
	v_mfma_f32_16x16x32_bf16 v[70:73], v[142:145], v[206:209], v[70:73]
	v_mfma_f32_16x16x32_bf16 v[110:113], v[134:137], v[214:217], v[110:113]
	v_mfma_f32_16x16x32_bf16 v[78:81], v[142:145], v[214:217], v[78:81]
	v_mfma_f32_16x16x32_bf16 v[26:29], v[146:149], v[162:165], v[26:29]
	v_mfma_f32_16x16x32_bf16 v[2:5], v[154:157], v[162:165], v[2:5]
	v_mfma_f32_16x16x32_bf16 v[34:37], v[146:149], v[170:173], v[34:37]
	v_mfma_f32_16x16x32_bf16 v[6:9], v[154:157], v[170:173], v[6:9]
	v_mfma_f32_16x16x32_bf16 v[38:41], v[146:149], v[202:205], v[38:41]
	v_mfma_f32_16x16x32_bf16 v[10:13], v[154:157], v[202:205], v[10:13]
	v_mfma_f32_16x16x32_bf16 v[46:49], v[146:149], v[210:213], v[46:49]
	v_mfma_f32_16x16x32_bf16 v[14:17], v[154:157], v[210:213], v[14:17]
	v_mfma_f32_16x16x32_bf16 v[26:29], v[150:153], v[166:169], v[26:29]
	v_mfma_f32_16x16x32_bf16 v[2:5], v[158:161], v[166:169], v[2:5]
	v_mfma_f32_16x16x32_bf16 v[34:37], v[150:153], v[174:177], v[34:37]
	v_mfma_f32_16x16x32_bf16 v[6:9], v[158:161], v[174:177], v[6:9]
	v_mfma_f32_16x16x32_bf16 v[38:41], v[150:153], v[206:209], v[38:41]
	v_mfma_f32_16x16x32_bf16 v[10:13], v[158:161], v[206:209], v[10:13]
	v_mfma_f32_16x16x32_bf16 v[46:49], v[150:153], v[214:217], v[46:49]
	v_mfma_f32_16x16x32_bf16 v[14:17], v[158:161], v[214:217], v[14:17]
	s_barrier
	s_add_i32 s18, s27, s15
	v_lshl_add_u64 v[218:219], v[218:219], 0, s[44:45]
	s_mov_b32 m0, s18
	ds_read_b128 v[162:165], v233 offset:49152
	ds_read_b128 v[166:169], v233 offset:50176
	ds_read_b128 v[170:173], v233 offset:51200
	ds_read_b128 v[174:177], v233 offset:52224
	ds_read_b128 v[202:205], v233 offset:53248
	ds_read_b128 v[206:209], v233 offset:54272
	ds_read_b128 v[210:213], v233 offset:55296
	ds_read_b128 v[214:217], v233 offset:56320
	global_load_lds_dwordx4 v[218:219], off
	s_add_i32 m0, s18, 0x2000
	s_add_u32 s16, s16, 0x100080
	v_lshl_add_u64 v[218:219], v[242:243], 0, s[44:45]
	s_addc_u32 s17, s17, 0
	s_add_i32 s18, s59, s15
	global_load_lds_dwordx4 v[218:219], off
	v_lshl_add_u64 v[218:219], s[16:17], 0, v[178:179]
	s_mov_b32 m0, s18
	s_nop 0
	global_load_lds_dwordx4 v[218:219], off
	v_lshl_add_u64 v[218:219], s[16:17], 0, v[180:181]
	s_add_i32 m0, s18, 0x2000
	s_nop 0
	global_load_lds_dwordx4 v[218:219], off
	v_lshl_add_u64 v[218:219], v[244:245], 0, s[44:45]
	s_mov_b32 m0, s66
	s_nop 0
	global_load_lds_dwordx4 v[218:219], off
	v_lshl_add_u64 v[218:219], v[246:247], 0, s[44:45]
	s_mov_b32 m0, s67
	s_nop 0
	global_load_lds_dwordx4 v[218:219], off
	s_waitcnt vmcnt(8)
	s_waitcnt lgkmcnt(0)
	s_barrier
	v_mfma_f32_16x16x32_bf16 v[114:117], v[130:133], v[162:165], v[114:117]
	v_mfma_f32_16x16x32_bf16 v[82:85], v[138:141], v[162:165], v[82:85]
	v_mfma_f32_16x16x32_bf16 v[118:121], v[130:133], v[170:173], v[118:121]
	v_mfma_f32_16x16x32_bf16 v[86:89], v[138:141], v[170:173], v[86:89]
	v_mfma_f32_16x16x32_bf16 v[122:125], v[130:133], v[202:205], v[122:125]
	v_mfma_f32_16x16x32_bf16 v[94:97], v[138:141], v[202:205], v[94:97]
	v_mfma_f32_16x16x32_bf16 v[126:129], v[130:133], v[210:213], v[126:129]
	v_mfma_f32_16x16x32_bf16 v[106:109], v[138:141], v[210:213], v[106:109]
	v_mfma_f32_16x16x32_bf16 v[114:117], v[134:137], v[166:169], v[114:117]
	v_mfma_f32_16x16x32_bf16 v[82:85], v[142:145], v[166:169], v[82:85]
	v_mfma_f32_16x16x32_bf16 v[118:121], v[134:137], v[174:177], v[118:121]
	v_mfma_f32_16x16x32_bf16 v[86:89], v[142:145], v[174:177], v[86:89]
	v_mfma_f32_16x16x32_bf16 v[122:125], v[134:137], v[206:209], v[122:125]
	v_mfma_f32_16x16x32_bf16 v[94:97], v[142:145], v[206:209], v[94:97]
	v_mfma_f32_16x16x32_bf16 v[126:129], v[134:137], v[214:217], v[126:129]
	v_mfma_f32_16x16x32_bf16 v[106:109], v[142:145], v[214:217], v[106:109]
	v_mfma_f32_16x16x32_bf16 v[50:53], v[146:149], v[162:165], v[50:53]
	v_mfma_f32_16x16x32_bf16 v[18:21], v[154:157], v[162:165], v[18:21]
	v_mfma_f32_16x16x32_bf16 v[54:57], v[146:149], v[170:173], v[54:57]
	v_mfma_f32_16x16x32_bf16 v[22:25], v[154:157], v[170:173], v[22:25]
	v_mfma_f32_16x16x32_bf16 v[62:65], v[146:149], v[202:205], v[62:65]
	v_mfma_f32_16x16x32_bf16 v[30:33], v[154:157], v[202:205], v[30:33]
	v_mfma_f32_16x16x32_bf16 v[74:77], v[146:149], v[210:213], v[74:77]
	v_mfma_f32_16x16x32_bf16 v[42:45], v[154:157], v[210:213], v[42:45]
	v_mfma_f32_16x16x32_bf16 v[50:53], v[150:153], v[166:169], v[50:53]
	v_mfma_f32_16x16x32_bf16 v[18:21], v[158:161], v[166:169], v[18:21]
	v_mfma_f32_16x16x32_bf16 v[54:57], v[150:153], v[174:177], v[54:57]
	v_mfma_f32_16x16x32_bf16 v[22:25], v[158:161], v[174:177], v[22:25]
	v_mfma_f32_16x16x32_bf16 v[62:65], v[150:153], v[206:209], v[62:65]
	v_mfma_f32_16x16x32_bf16 v[30:33], v[158:161], v[206:209], v[30:33]
	v_mfma_f32_16x16x32_bf16 v[74:77], v[150:153], v[214:217], v[74:77]
	v_mfma_f32_16x16x32_bf16 v[42:45], v[158:161], v[214:217], v[42:45]
	s_barrier
	s_add_i32 s26, s26, 2
	s_add_u32 s0, s0, 0x100
	s_addc_u32 s1, s1, 0
	s_add_u32 s24, s24, 0x100
	s_addc_u32 s25, s25, 0
	s_cmp_gt_u32 s26, 61
	s_cbranch_scc0 .LBB0_672
	s_and_b64 vcc, exec, s[90:91]
	s_cbranch_vccz .LBB0_675
	s_barrier

.Lpeelc:
	ds_read_b128 v[156:159], v153
	ds_read_b128 v[160:163], v153 offset:1024
	ds_read_b128 v[164:167], v153 offset:2048
	ds_read_b128 v[168:171], v153 offset:3072
	ds_read_b128 v[172:175], v154
	ds_read_b128 v[176:179], v154 offset:1024
	ds_read_b128 v[180:183], v154 offset:2048
	ds_read_b128 v[184:187], v154 offset:3072
	s_add_u32 s36, s26, 0xfff00080
	s_addc_u32 s37, s27, -1
	s_cmp_eq_u32 s54, 60
	s_cselect_b32 s39, s19, s37
	s_cselect_b32 s38, s50, s36
	s_cselect_b32 s37, s17, s53
	s_cselect_b32 s36, s51, s52
	v_lshl_add_u64 v[148:149], s[26:27], 0, v[140:141]
	s_add_i32 m0, s25, 0xc000
	ds_read_b128 v[188:191], v155
	ds_read_b128 v[192:195], v155 offset:1024
	ds_read_b128 v[196:199], v155 offset:2048
	ds_read_b128 v[200:203], v155 offset:3072
	ds_read_b128 v[204:207], v155 offset:4096
	ds_read_b128 v[208:211], v155 offset:5120
	ds_read_b128 v[212:215], v155 offset:6144
	ds_read_b128 v[216:219], v155 offset:7168
	global_load_lds_dwordx4 v[148:149], off
	v_lshl_add_u64 v[148:149], s[26:27], 0, v[142:143]
	s_add_i32 m0, s25, 0xe000
	s_nop 0
	global_load_lds_dwordx4 v[148:149], off
	s_waitcnt vmcnt(8)
	s_waitcnt lgkmcnt(0)
	s_barrier
	v_mfma_f32_16x16x32_bf16 v[126:129], v[156:159], v[188:191], 0
	v_mfma_f32_16x16x32_bf16 v[122:125], v[164:167], v[188:191], 0
	v_mfma_f32_16x16x32_bf16 v[118:121], v[156:159], v[196:199], 0
	v_mfma_f32_16x16x32_bf16 v[114:117], v[164:167], v[196:199], 0
	v_mfma_f32_16x16x32_bf16 v[94:97], v[156:159], v[204:207], 0
	v_mfma_f32_16x16x32_bf16 v[90:93], v[164:167], v[204:207], 0
	v_mfma_f32_16x16x32_bf16 v[86:89], v[156:159], v[212:215], 0
	v_mfma_f32_16x16x32_bf16 v[82:85], v[164:167], v[212:215], 0
	v_mfma_f32_16x16x32_bf16 v[126:129], v[160:163], v[192:195], v[126:129]
	v_mfma_f32_16x16x32_bf16 v[122:125], v[168:171], v[192:195], v[122:125]
	v_mfma_f32_16x16x32_bf16 v[118:121], v[160:163], v[200:203], v[118:121]
	v_mfma_f32_16x16x32_bf16 v[114:117], v[168:171], v[200:203], v[114:117]
	v_mfma_f32_16x16x32_bf16 v[94:97], v[160:163], v[208:211], v[94:97]
	v_mfma_f32_16x16x32_bf16 v[90:93], v[168:171], v[208:211], v[90:93]
	v_mfma_f32_16x16x32_bf16 v[86:89], v[160:163], v[216:219], v[86:89]
	v_mfma_f32_16x16x32_bf16 v[82:85], v[168:171], v[216:219], v[82:85]
	v_mfma_f32_16x16x32_bf16 v[110:113], v[172:175], v[188:191], 0
	v_mfma_f32_16x16x32_bf16 v[106:109], v[180:183], v[188:191], 0
	v_mfma_f32_16x16x32_bf16 v[102:105], v[172:175], v[196:199], 0
	v_mfma_f32_16x16x32_bf16 v[98:101], v[180:183], v[196:199], 0
	v_mfma_f32_16x16x32_bf16 v[78:81], v[172:175], v[204:207], 0
	v_mfma_f32_16x16x32_bf16 v[74:77], v[180:183], v[204:207], 0
	v_mfma_f32_16x16x32_bf16 v[70:73], v[172:175], v[212:215], 0
	v_mfma_f32_16x16x32_bf16 v[66:69], v[180:183], v[212:215], 0
	v_mfma_f32_16x16x32_bf16 v[110:113], v[176:179], v[192:195], v[110:113]
	v_mfma_f32_16x16x32_bf16 v[106:109], v[184:187], v[192:195], v[106:109]
	v_mfma_f32_16x16x32_bf16 v[102:105], v[176:179], v[200:203], v[102:105]
	v_mfma_f32_16x16x32_bf16 v[98:101], v[184:187], v[200:203], v[98:101]
	v_mfma_f32_16x16x32_bf16 v[78:81], v[176:179], v[208:211], v[78:81]
	v_mfma_f32_16x16x32_bf16 v[74:77], v[184:187], v[208:211], v[74:77]
	v_mfma_f32_16x16x32_bf16 v[70:73], v[176:179], v[216:219], v[70:73]
	v_mfma_f32_16x16x32_bf16 v[66:69], v[184:187], v[216:219], v[66:69]
	s_barrier
	s_add_i32 s55, s44, s13
	v_lshl_add_u64 v[148:149], s[36:37], 0, v[134:135]
	s_mov_b32 m0, s55
	ds_read_b128 v[188:191], v155 offset:16384
	ds_read_b128 v[192:195], v155 offset:17408
	ds_read_b128 v[196:199], v155 offset:18432
	ds_read_b128 v[200:203], v155 offset:19456
	ds_read_b128 v[204:207], v155 offset:20480
	ds_read_b128 v[208:211], v155 offset:21504
	ds_read_b128 v[212:215], v155 offset:22528
	ds_read_b128 v[216:219], v155 offset:23552
	global_load_lds_dwordx4 v[148:149], off
	s_add_i32 m0, s55, 0x2000
	s_add_u32 s56, s36, 0x100000
	v_lshl_add_u64 v[220:221], s[36:37], 0, v[130:131]
	s_addc_u32 s57, s37, 0
	s_add_i32 s55, s45, s13
	global_load_lds_dwordx4 v[220:221], off
	v_lshl_add_u64 v[224:225], s[56:57], 0, v[134:135]
	s_mov_b32 m0, s55
	v_lshl_add_u64 v[226:227], s[38:39], 0, v[132:133]
	global_load_lds_dwordx4 v[224:225], off
	v_lshl_add_u64 v[224:225], s[56:57], 0, v[130:131]
	s_add_i32 m0, s55, 0x2000
	s_nop 0
	global_load_lds_dwordx4 v[224:225], off
	v_lshl_add_u64 v[224:225], s[38:39], 0, v[136:137]
	s_mov_b32 m0, s25
	s_nop 0
	global_load_lds_dwordx4 v[224:225], off
	s_mov_b32 m0, s31
	s_nop 0
	global_load_lds_dwordx4 v[226:227], off
	s_waitcnt vmcnt(8)
	s_waitcnt lgkmcnt(0)
	s_barrier
	v_mfma_f32_16x16x32_bf16 v[62:65], v[156:159], v[188:191], 0
	v_mfma_f32_16x16x32_bf16 v[58:61], v[164:167], v[188:191], 0
	v_mfma_f32_16x16x32_bf16 v[54:57], v[156:159], v[196:199], 0
	v_mfma_f32_16x16x32_bf16 v[50:53], v[164:167], v[196:199], 0
	v_mfma_f32_16x16x32_bf16 v[30:33], v[156:159], v[204:207], 0
	v_mfma_f32_16x16x32_bf16 v[26:29], v[164:167], v[204:207], 0
	v_mfma_f32_16x16x32_bf16 v[22:25], v[156:159], v[212:215], 0
	v_mfma_f32_16x16x32_bf16 v[18:21], v[164:167], v[212:215], 0
	v_mfma_f32_16x16x32_bf16 v[62:65], v[160:163], v[192:195], v[62:65]
	v_mfma_f32_16x16x32_bf16 v[58:61], v[168:171], v[192:195], v[58:61]
	v_mfma_f32_16x16x32_bf16 v[54:57], v[160:163], v[200:203], v[54:57]
	v_mfma_f32_16x16x32_bf16 v[50:53], v[168:171], v[200:203], v[50:53]
	v_mfma_f32_16x16x32_bf16 v[30:33], v[160:163], v[208:211], v[30:33]
	v_mfma_f32_16x16x32_bf16 v[26:29], v[168:171], v[208:211], v[26:29]
	v_mfma_f32_16x16x32_bf16 v[22:25], v[160:163], v[216:219], v[22:25]
	v_mfma_f32_16x16x32_bf16 v[18:21], v[168:171], v[216:219], v[18:21]
	v_mfma_f32_16x16x32_bf16 v[46:49], v[172:175], v[188:191], 0
	v_mfma_f32_16x16x32_bf16 v[42:45], v[180:183], v[188:191], 0
	v_mfma_f32_16x16x32_bf16 v[38:41], v[172:175], v[196:199], 0
	v_mfma_f32_16x16x32_bf16 v[34:37], v[180:183], v[196:199], 0
	v_mfma_f32_16x16x32_bf16 v[14:17], v[172:175], v[204:207], 0
	v_mfma_f32_16x16x32_bf16 v[10:13], v[180:183], v[204:207], 0
	v_mfma_f32_16x16x32_bf16 v[6:9], v[172:175], v[212:215], 0
	v_mfma_f32_16x16x32_bf16 v[2:5], v[180:183], v[212:215], 0
	v_mfma_f32_16x16x32_bf16 v[46:49], v[176:179], v[192:195], v[46:49]
	v_mfma_f32_16x16x32_bf16 v[42:45], v[184:187], v[192:195], v[42:45]
	v_mfma_f32_16x16x32_bf16 v[38:41], v[176:179], v[200:203], v[38:41]
	v_mfma_f32_16x16x32_bf16 v[34:37], v[184:187], v[200:203], v[34:37]
	v_mfma_f32_16x16x32_bf16 v[14:17], v[176:179], v[208:211], v[14:17]
	v_mfma_f32_16x16x32_bf16 v[10:13], v[184:187], v[208:211], v[10:13]
	v_mfma_f32_16x16x32_bf16 v[6:9], v[176:179], v[216:219], v[6:9]
	v_mfma_f32_16x16x32_bf16 v[2:5], v[184:187], v[216:219], v[2:5]
	s_barrier
	s_add_i32 s55, 0, 0x18000
	s_add_i32 s56, 0, 0x1c000
	v_add_u32_e32 v168, s55, v151
	v_add_u32_e32 v184, s56, v151
	ds_read_b128 v[156:159], v168
	ds_read_b128 v[160:163], v168 offset:1024
	ds_read_b128 v[164:167], v168 offset:2048
	ds_read_b128 v[168:171], v168 offset:3072
	ds_read_b128 v[172:175], v184
	ds_read_b128 v[176:179], v184 offset:1024
	ds_read_b128 v[180:183], v184 offset:2048
	ds_read_b128 v[184:187], v184 offset:3072
	s_add_u32 s38, s38, 0x100000
	s_addc_u32 s39, s39, 0
	s_mov_b32 m0, s34
	v_lshl_add_u64 v[228:229], s[38:39], 0, v[136:137]
	ds_read_b128 v[188:191], v155 offset:32768
	ds_read_b128 v[192:195], v155 offset:33792
	ds_read_b128 v[196:199], v155 offset:34816
	ds_read_b128 v[200:203], v155 offset:35840
	ds_read_b128 v[204:207], v155 offset:36864
	ds_read_b128 v[208:211], v155 offset:37888
	ds_read_b128 v[212:215], v155 offset:38912
	ds_read_b128 v[216:219], v155 offset:39936
	global_load_lds_dwordx4 v[228:229], off
	v_lshl_add_u64 v[228:229], s[38:39], 0, v[132:133]
	s_mov_b32 m0, s35
	s_nop 0
	global_load_lds_dwordx4 v[228:229], off
	s_waitcnt vmcnt(8)
	s_waitcnt lgkmcnt(0)
	s_barrier
	v_mfma_f32_16x16x32_bf16 v[126:129], v[156:159], v[188:191], v[126:129]
	v_mfma_f32_16x16x32_bf16 v[122:125], v[164:167], v[188:191], v[122:125]
	v_mfma_f32_16x16x32_bf16 v[118:121], v[156:159], v[196:199], v[118:121]
	v_mfma_f32_16x16x32_bf16 v[114:117], v[164:167], v[196:199], v[114:117]
	v_mfma_f32_16x16x32_bf16 v[94:97], v[156:159], v[204:207], v[94:97]
	v_mfma_f32_16x16x32_bf16 v[90:93], v[164:167], v[204:207], v[90:93]
	v_mfma_f32_16x16x32_bf16 v[86:89], v[156:159], v[212:215], v[86:89]
	v_mfma_f32_16x16x32_bf16 v[82:85], v[164:167], v[212:215], v[82:85]
	v_mfma_f32_16x16x32_bf16 v[126:129], v[160:163], v[192:195], v[126:129]
	v_mfma_f32_16x16x32_bf16 v[122:125], v[168:171], v[192:195], v[122:125]
	v_mfma_f32_16x16x32_bf16 v[118:121], v[160:163], v[200:203], v[118:121]
	v_mfma_f32_16x16x32_bf16 v[114:117], v[168:171], v[200:203], v[114:117]
	v_mfma_f32_16x16x32_bf16 v[94:97], v[160:163], v[208:211], v[94:97]
	v_mfma_f32_16x16x32_bf16 v[90:93], v[168:171], v[208:211], v[90:93]
	v_mfma_f32_16x16x32_bf16 v[86:89], v[160:163], v[216:219], v[86:89]
	v_mfma_f32_16x16x32_bf16 v[82:85], v[168:171], v[216:219], v[82:85]
	v_mfma_f32_16x16x32_bf16 v[110:113], v[172:175], v[188:191], v[110:113]
	v_mfma_f32_16x16x32_bf16 v[106:109], v[180:183], v[188:191], v[106:109]
	v_mfma_f32_16x16x32_bf16 v[102:105], v[172:175], v[196:199], v[102:105]
	v_mfma_f32_16x16x32_bf16 v[98:101], v[180:183], v[196:199], v[98:101]
	v_mfma_f32_16x16x32_bf16 v[78:81], v[172:175], v[204:207], v[78:81]
	v_mfma_f32_16x16x32_bf16 v[74:77], v[180:183], v[204:207], v[74:77]
	v_mfma_f32_16x16x32_bf16 v[70:73], v[172:175], v[212:215], v[70:73]
	v_mfma_f32_16x16x32_bf16 v[66:69], v[180:183], v[212:215], v[66:69]
	v_mfma_f32_16x16x32_bf16 v[110:113], v[176:179], v[192:195], v[110:113]
	v_mfma_f32_16x16x32_bf16 v[106:109], v[184:187], v[192:195], v[106:109]
	v_mfma_f32_16x16x32_bf16 v[102:105], v[176:179], v[200:203], v[102:105]
	v_mfma_f32_16x16x32_bf16 v[98:101], v[184:187], v[200:203], v[98:101]
	v_mfma_f32_16x16x32_bf16 v[78:81], v[176:179], v[208:211], v[78:81]
	v_mfma_f32_16x16x32_bf16 v[74:77], v[184:187], v[208:211], v[74:77]
	v_mfma_f32_16x16x32_bf16 v[70:73], v[176:179], v[216:219], v[70:73]
	v_mfma_f32_16x16x32_bf16 v[66:69], v[184:187], v[216:219], v[66:69]
	s_barrier
	s_add_i32 s38, s55, s13
	v_lshl_add_u64 v[148:149], v[148:149], 0, s[6:7]
	s_mov_b32 m0, s38
	ds_read_b128 v[188:191], v155 offset:49152
	ds_read_b128 v[192:195], v155 offset:50176
	ds_read_b128 v[196:199], v155 offset:51200
	ds_read_b128 v[200:203], v155 offset:52224
	ds_read_b128 v[204:207], v155 offset:53248
	ds_read_b128 v[208:211], v155 offset:54272
	ds_read_b128 v[212:215], v155 offset:55296
	ds_read_b128 v[216:219], v155 offset:56320
	global_load_lds_dwordx4 v[148:149], off
	s_add_i32 m0, s38, 0x2000
	s_add_u32 s36, s36, 0x100080
	v_lshl_add_u64 v[148:149], v[220:221], 0, s[6:7]
	s_addc_u32 s37, s37, 0
	s_add_i32 s38, s56, s13
	global_load_lds_dwordx4 v[148:149], off
	v_lshl_add_u64 v[148:149], s[36:37], 0, v[134:135]
	s_mov_b32 m0, s38
	s_nop 0
	global_load_lds_dwordx4 v[148:149], off
	v_lshl_add_u64 v[148:149], s[36:37], 0, v[130:131]
	s_add_i32 m0, s38, 0x2000
	s_nop 0
	global_load_lds_dwordx4 v[148:149], off
	v_lshl_add_u64 v[148:149], v[224:225], 0, s[6:7]
	s_mov_b32 m0, s41
	s_nop 0
	global_load_lds_dwordx4 v[148:149], off
	v_lshl_add_u64 v[148:149], v[226:227], 0, s[6:7]
	s_mov_b32 m0, s42
	s_nop 0
	global_load_lds_dwordx4 v[148:149], off
	s_waitcnt vmcnt(8)
	s_waitcnt lgkmcnt(0)
	s_barrier
	v_mfma_f32_16x16x32_bf16 v[62:65], v[156:159], v[188:191], v[62:65]
	v_mfma_f32_16x16x32_bf16 v[58:61], v[164:167], v[188:191], v[58:61]
	v_mfma_f32_16x16x32_bf16 v[54:57], v[156:159], v[196:199], v[54:57]
	v_mfma_f32_16x16x32_bf16 v[50:53], v[164:167], v[196:199], v[50:53]
	v_mfma_f32_16x16x32_bf16 v[30:33], v[156:159], v[204:207], v[30:33]
	v_mfma_f32_16x16x32_bf16 v[26:29], v[164:167], v[204:207], v[26:29]
	v_mfma_f32_16x16x32_bf16 v[22:25], v[156:159], v[212:215], v[22:25]
	v_mfma_f32_16x16x32_bf16 v[18:21], v[164:167], v[212:215], v[18:21]
	v_mfma_f32_16x16x32_bf16 v[62:65], v[160:163], v[192:195], v[62:65]
	v_mfma_f32_16x16x32_bf16 v[58:61], v[168:171], v[192:195], v[58:61]
	v_mfma_f32_16x16x32_bf16 v[54:57], v[160:163], v[200:203], v[54:57]
	v_mfma_f32_16x16x32_bf16 v[50:53], v[168:171], v[200:203], v[50:53]
	v_mfma_f32_16x16x32_bf16 v[30:33], v[160:163], v[208:211], v[30:33]
	v_mfma_f32_16x16x32_bf16 v[26:29], v[168:171], v[208:211], v[26:29]
	v_mfma_f32_16x16x32_bf16 v[22:25], v[160:163], v[216:219], v[22:25]
	v_mfma_f32_16x16x32_bf16 v[18:21], v[168:171], v[216:219], v[18:21]
	v_mfma_f32_16x16x32_bf16 v[46:49], v[172:175], v[188:191], v[46:49]
	v_mfma_f32_16x16x32_bf16 v[42:45], v[180:183], v[188:191], v[42:45]
	v_mfma_f32_16x16x32_bf16 v[38:41], v[172:175], v[196:199], v[38:41]
	v_mfma_f32_16x16x32_bf16 v[34:37], v[180:183], v[196:199], v[34:37]
	v_mfma_f32_16x16x32_bf16 v[14:17], v[172:175], v[204:207], v[14:17]
	v_mfma_f32_16x16x32_bf16 v[10:13], v[180:183], v[204:207], v[10:13]
	v_mfma_f32_16x16x32_bf16 v[6:9], v[172:175], v[212:215], v[6:9]
	v_mfma_f32_16x16x32_bf16 v[2:5], v[180:183], v[212:215], v[2:5]
	v_mfma_f32_16x16x32_bf16 v[46:49], v[176:179], v[192:195], v[46:49]
	v_mfma_f32_16x16x32_bf16 v[42:45], v[184:187], v[192:195], v[42:45]
	v_mfma_f32_16x16x32_bf16 v[38:41], v[176:179], v[200:203], v[38:41]
	v_mfma_f32_16x16x32_bf16 v[34:37], v[184:187], v[200:203], v[34:37]
	v_mfma_f32_16x16x32_bf16 v[14:17], v[176:179], v[208:211], v[14:17]
	v_mfma_f32_16x16x32_bf16 v[10:13], v[184:187], v[208:211], v[10:13]
	v_mfma_f32_16x16x32_bf16 v[6:9], v[176:179], v[216:219], v[6:9]
	v_mfma_f32_16x16x32_bf16 v[2:5], v[184:187], v[216:219], v[2:5]
	s_barrier
	s_add_i32 s54, s54, 2
	s_add_u32 s26, s26, 0x100
	s_addc_u32 s27, s27, 0
	s_add_u32 s52, s52, 0x100
	s_addc_u32 s53, s53, 0
.LBB0_788:
	ds_read_b128 v[156:159], v153
	ds_read_b128 v[160:163], v153 offset:1024
	ds_read_b128 v[164:167], v153 offset:2048
	ds_read_b128 v[168:171], v153 offset:3072
	ds_read_b128 v[172:175], v154
	ds_read_b128 v[176:179], v154 offset:1024
	ds_read_b128 v[180:183], v154 offset:2048
	ds_read_b128 v[184:187], v154 offset:3072
	s_add_u32 s36, s26, 0xfff00080
	s_addc_u32 s37, s27, -1
	s_cmp_eq_u32 s54, 60
	s_cselect_b32 s39, s19, s37
	s_cselect_b32 s38, s50, s36
	s_cselect_b32 s37, s17, s53
	s_cselect_b32 s36, s51, s52
	v_lshl_add_u64 v[148:149], s[26:27], 0, v[140:141]
	s_add_i32 m0, s25, 0xc000
	ds_read_b128 v[188:191], v155
	ds_read_b128 v[192:195], v155 offset:1024
	ds_read_b128 v[196:199], v155 offset:2048
	ds_read_b128 v[200:203], v155 offset:3072
	ds_read_b128 v[204:207], v155 offset:4096
	ds_read_b128 v[208:211], v155 offset:5120
	ds_read_b128 v[212:215], v155 offset:6144
	ds_read_b128 v[216:219], v155 offset:7168
	global_load_lds_dwordx4 v[148:149], off
	v_lshl_add_u64 v[148:149], s[26:27], 0, v[142:143]
	s_add_i32 m0, s25, 0xe000
	s_nop 0
	global_load_lds_dwordx4 v[148:149], off
	s_waitcnt vmcnt(8)
	s_waitcnt lgkmcnt(0)
	s_barrier
	v_mfma_f32_16x16x32_bf16 v[126:129], v[156:159], v[188:191], v[126:129]
	v_mfma_f32_16x16x32_bf16 v[122:125], v[164:167], v[188:191], v[122:125]
	v_mfma_f32_16x16x32_bf16 v[118:121], v[156:159], v[196:199], v[118:121]
	v_mfma_f32_16x16x32_bf16 v[114:117], v[164:167], v[196:199], v[114:117]
	v_mfma_f32_16x16x32_bf16 v[94:97], v[156:159], v[204:207], v[94:97]
	v_mfma_f32_16x16x32_bf16 v[90:93], v[164:167], v[204:207], v[90:93]
	v_mfma_f32_16x16x32_bf16 v[86:89], v[156:159], v[212:215], v[86:89]
	v_mfma_f32_16x16x32_bf16 v[82:85], v[164:167], v[212:215], v[82:85]
	v_mfma_f32_16x16x32_bf16 v[126:129], v[160:163], v[192:195], v[126:129]
	v_mfma_f32_16x16x32_bf16 v[122:125], v[168:171], v[192:195], v[122:125]
	v_mfma_f32_16x16x32_bf16 v[118:121], v[160:163], v[200:203], v[118:121]
	v_mfma_f32_16x16x32_bf16 v[114:117], v[168:171], v[200:203], v[114:117]
	v_mfma_f32_16x16x32_bf16 v[94:97], v[160:163], v[208:211], v[94:97]
	v_mfma_f32_16x16x32_bf16 v[90:93], v[168:171], v[208:211], v[90:93]
	v_mfma_f32_16x16x32_bf16 v[86:89], v[160:163], v[216:219], v[86:89]
	v_mfma_f32_16x16x32_bf16 v[82:85], v[168:171], v[216:219], v[82:85]
	v_mfma_f32_16x16x32_bf16 v[110:113], v[172:175], v[188:191], v[110:113]
	v_mfma_f32_16x16x32_bf16 v[106:109], v[180:183], v[188:191], v[106:109]
	v_mfma_f32_16x16x32_bf16 v[102:105], v[172:175], v[196:199], v[102:105]
	v_mfma_f32_16x16x32_bf16 v[98:101], v[180:183], v[196:199], v[98:101]
	v_mfma_f32_16x16x32_bf16 v[78:81], v[172:175], v[204:207], v[78:81]
	v_mfma_f32_16x16x32_bf16 v[74:77], v[180:183], v[204:207], v[74:77]
	v_mfma_f32_16x16x32_bf16 v[70:73], v[172:175], v[212:215], v[70:73]
	v_mfma_f32_16x16x32_bf16 v[66:69], v[180:183], v[212:215], v[66:69]
	v_mfma_f32_16x16x32_bf16 v[110:113], v[176:179], v[192:195], v[110:113]
	v_mfma_f32_16x16x32_bf16 v[106:109], v[184:187], v[192:195], v[106:109]
	v_mfma_f32_16x16x32_bf16 v[102:105], v[176:179], v[200:203], v[102:105]
	v_mfma_f32_16x16x32_bf16 v[98:101], v[184:187], v[200:203], v[98:101]
	v_mfma_f32_16x16x32_bf16 v[78:81], v[176:179], v[208:211], v[78:81]
	v_mfma_f32_16x16x32_bf16 v[74:77], v[184:187], v[208:211], v[74:77]
	v_mfma_f32_16x16x32_bf16 v[70:73], v[176:179], v[216:219], v[70:73]
	v_mfma_f32_16x16x32_bf16 v[66:69], v[184:187], v[216:219], v[66:69]
	s_barrier
	s_add_i32 s55, s44, s13
	v_lshl_add_u64 v[148:149], s[36:37], 0, v[134:135]
	s_mov_b32 m0, s55
	ds_read_b128 v[188:191], v155 offset:16384
	ds_read_b128 v[192:195], v155 offset:17408
	ds_read_b128 v[196:199], v155 offset:18432
	ds_read_b128 v[200:203], v155 offset:19456
	ds_read_b128 v[204:207], v155 offset:20480
	ds_read_b128 v[208:211], v155 offset:21504
	ds_read_b128 v[212:215], v155 offset:22528
	ds_read_b128 v[216:219], v155 offset:23552
	global_load_lds_dwordx4 v[148:149], off
	s_add_i32 m0, s55, 0x2000
	s_add_u32 s56, s36, 0x100000
	v_lshl_add_u64 v[220:221], s[36:37], 0, v[130:131]
	s_addc_u32 s57, s37, 0
	s_add_i32 s55, s45, s13
	global_load_lds_dwordx4 v[220:221], off
	v_lshl_add_u64 v[224:225], s[56:57], 0, v[134:135]
	s_mov_b32 m0, s55
	v_lshl_add_u64 v[226:227], s[38:39], 0, v[132:133]
	global_load_lds_dwordx4 v[224:225], off
	v_lshl_add_u64 v[224:225], s[56:57], 0, v[130:131]
	s_add_i32 m0, s55, 0x2000
	s_nop 0
	global_load_lds_dwordx4 v[224:225], off
	v_lshl_add_u64 v[224:225], s[38:39], 0, v[136:137]
	s_mov_b32 m0, s25
	s_nop 0
	global_load_lds_dwordx4 v[224:225], off
	s_mov_b32 m0, s31
	s_nop 0
	global_load_lds_dwordx4 v[226:227], off
	s_waitcnt vmcnt(8)
	s_waitcnt lgkmcnt(0)
	s_barrier
	v_mfma_f32_16x16x32_bf16 v[62:65], v[156:159], v[188:191], v[62:65]
	v_mfma_f32_16x16x32_bf16 v[58:61], v[164:167], v[188:191], v[58:61]
	v_mfma_f32_16x16x32_bf16 v[54:57], v[156:159], v[196:199], v[54:57]
	v_mfma_f32_16x16x32_bf16 v[50:53], v[164:167], v[196:199], v[50:53]
	v_mfma_f32_16x16x32_bf16 v[30:33], v[156:159], v[204:207], v[30:33]
	v_mfma_f32_16x16x32_bf16 v[26:29], v[164:167], v[204:207], v[26:29]
	v_mfma_f32_16x16x32_bf16 v[22:25], v[156:159], v[212:215], v[22:25]
	v_mfma_f32_16x16x32_bf16 v[18:21], v[164:167], v[212:215], v[18:21]
	v_mfma_f32_16x16x32_bf16 v[62:65], v[160:163], v[192:195], v[62:65]
	v_mfma_f32_16x16x32_bf16 v[58:61], v[168:171], v[192:195], v[58:61]
	v_mfma_f32_16x16x32_bf16 v[54:57], v[160:163], v[200:203], v[54:57]
	v_mfma_f32_16x16x32_bf16 v[50:53], v[168:171], v[200:203], v[50:53]
	v_mfma_f32_16x16x32_bf16 v[30:33], v[160:163], v[208:211], v[30:33]
	v_mfma_f32_16x16x32_bf16 v[26:29], v[168:171], v[208:211], v[26:29]
	v_mfma_f32_16x16x32_bf16 v[22:25], v[160:163], v[216:219], v[22:25]
	v_mfma_f32_16x16x32_bf16 v[18:21], v[168:171], v[216:219], v[18:21]
	v_mfma_f32_16x16x32_bf16 v[46:49], v[172:175], v[188:191], v[46:49]
	v_mfma_f32_16x16x32_bf16 v[42:45], v[180:183], v[188:191], v[42:45]
	v_mfma_f32_16x16x32_bf16 v[38:41], v[172:175], v[196:199], v[38:41]
	v_mfma_f32_16x16x32_bf16 v[34:37], v[180:183], v[196:199], v[34:37]
	v_mfma_f32_16x16x32_bf16 v[14:17], v[172:175], v[204:207], v[14:17]
	v_mfma_f32_16x16x32_bf16 v[10:13], v[180:183], v[204:207], v[10:13]
	v_mfma_f32_16x16x32_bf16 v[6:9], v[172:175], v[212:215], v[6:9]
	v_mfma_f32_16x16x32_bf16 v[2:5], v[180:183], v[212:215], v[2:5]
	v_mfma_f32_16x16x32_bf16 v[46:49], v[176:179], v[192:195], v[46:49]
	v_mfma_f32_16x16x32_bf16 v[42:45], v[184:187], v[192:195], v[42:45]
	v_mfma_f32_16x16x32_bf16 v[38:41], v[176:179], v[200:203], v[38:41]
	v_mfma_f32_16x16x32_bf16 v[34:37], v[184:187], v[200:203], v[34:37]
	v_mfma_f32_16x16x32_bf16 v[14:17], v[176:179], v[208:211], v[14:17]
	v_mfma_f32_16x16x32_bf16 v[10:13], v[184:187], v[208:211], v[10:13]
	v_mfma_f32_16x16x32_bf16 v[6:9], v[176:179], v[216:219], v[6:9]
	v_mfma_f32_16x16x32_bf16 v[2:5], v[184:187], v[216:219], v[2:5]
	s_barrier
	s_add_i32 s55, 0, 0x18000
	s_add_i32 s56, 0, 0x1c000
	v_add_u32_e32 v168, s55, v151
	v_add_u32_e32 v184, s56, v151
	ds_read_b128 v[156:159], v168
	ds_read_b128 v[160:163], v168 offset:1024
	ds_read_b128 v[164:167], v168 offset:2048
	ds_read_b128 v[168:171], v168 offset:3072
	ds_read_b128 v[172:175], v184
	ds_read_b128 v[176:179], v184 offset:1024
	ds_read_b128 v[180:183], v184 offset:2048
	ds_read_b128 v[184:187], v184 offset:3072
	s_add_u32 s38, s38, 0x100000
	s_addc_u32 s39, s39, 0
	s_mov_b32 m0, s34
	v_lshl_add_u64 v[228:229], s[38:39], 0, v[136:137]
	ds_read_b128 v[188:191], v155 offset:32768
	ds_read_b128 v[192:195], v155 offset:33792
	ds_read_b128 v[196:199], v155 offset:34816
	ds_read_b128 v[200:203], v155 offset:35840
	ds_read_b128 v[204:207], v155 offset:36864
	ds_read_b128 v[208:211], v155 offset:37888
	ds_read_b128 v[212:215], v155 offset:38912
	ds_read_b128 v[216:219], v155 offset:39936
	global_load_lds_dwordx4 v[228:229], off
	v_lshl_add_u64 v[228:229], s[38:39], 0, v[132:133]
	s_mov_b32 m0, s35
	s_nop 0
	global_load_lds_dwordx4 v[228:229], off
	s_waitcnt vmcnt(8)
	s_waitcnt lgkmcnt(0)
	s_barrier
	v_mfma_f32_16x16x32_bf16 v[126:129], v[156:159], v[188:191], v[126:129]
	v_mfma_f32_16x16x32_bf16 v[122:125], v[164:167], v[188:191], v[122:125]
	v_mfma_f32_16x16x32_bf16 v[118:121], v[156:159], v[196:199], v[118:121]
	v_mfma_f32_16x16x32_bf16 v[114:117], v[164:167], v[196:199], v[114:117]
	v_mfma_f32_16x16x32_bf16 v[94:97], v[156:159], v[204:207], v[94:97]
	v_mfma_f32_16x16x32_bf16 v[90:93], v[164:167], v[204:207], v[90:93]
	v_mfma_f32_16x16x32_bf16 v[86:89], v[156:159], v[212:215], v[86:89]
	v_mfma_f32_16x16x32_bf16 v[82:85], v[164:167], v[212:215], v[82:85]
	v_mfma_f32_16x16x32_bf16 v[126:129], v[160:163], v[192:195], v[126:129]
	v_mfma_f32_16x16x32_bf16 v[122:125], v[168:171], v[192:195], v[122:125]
	v_mfma_f32_16x16x32_bf16 v[118:121], v[160:163], v[200:203], v[118:121]
	v_mfma_f32_16x16x32_bf16 v[114:117], v[168:171], v[200:203], v[114:117]
	v_mfma_f32_16x16x32_bf16 v[94:97], v[160:163], v[208:211], v[94:97]
	v_mfma_f32_16x16x32_bf16 v[90:93], v[168:171], v[208:211], v[90:93]
	v_mfma_f32_16x16x32_bf16 v[86:89], v[160:163], v[216:219], v[86:89]
	v_mfma_f32_16x16x32_bf16 v[82:85], v[168:171], v[216:219], v[82:85]
	v_mfma_f32_16x16x32_bf16 v[110:113], v[172:175], v[188:191], v[110:113]
	v_mfma_f32_16x16x32_bf16 v[106:109], v[180:183], v[188:191], v[106:109]
	v_mfma_f32_16x16x32_bf16 v[102:105], v[172:175], v[196:199], v[102:105]
	v_mfma_f32_16x16x32_bf16 v[98:101], v[180:183], v[196:199], v[98:101]
	v_mfma_f32_16x16x32_bf16 v[78:81], v[172:175], v[204:207], v[78:81]
	v_mfma_f32_16x16x32_bf16 v[74:77], v[180:183], v[204:207], v[74:77]
	v_mfma_f32_16x16x32_bf16 v[70:73], v[172:175], v[212:215], v[70:73]
	v_mfma_f32_16x16x32_bf16 v[66:69], v[180:183], v[212:215], v[66:69]
	v_mfma_f32_16x16x32_bf16 v[110:113], v[176:179], v[192:195], v[110:113]
	v_mfma_f32_16x16x32_bf16 v[106:109], v[184:187], v[192:195], v[106:109]
	v_mfma_f32_16x16x32_bf16 v[102:105], v[176:179], v[200:203], v[102:105]
	v_mfma_f32_16x16x32_bf16 v[98:101], v[184:187], v[200:203], v[98:101]
	v_mfma_f32_16x16x32_bf16 v[78:81], v[176:179], v[208:211], v[78:81]
	v_mfma_f32_16x16x32_bf16 v[74:77], v[184:187], v[208:211], v[74:77]
	v_mfma_f32_16x16x32_bf16 v[70:73], v[176:179], v[216:219], v[70:73]
	v_mfma_f32_16x16x32_bf16 v[66:69], v[184:187], v[216:219], v[66:69]
	s_barrier
	s_add_i32 s38, s55, s13
	v_lshl_add_u64 v[148:149], v[148:149], 0, s[6:7]
	s_mov_b32 m0, s38
	ds_read_b128 v[188:191], v155 offset:49152
	ds_read_b128 v[192:195], v155 offset:50176
	ds_read_b128 v[196:199], v155 offset:51200
	ds_read_b128 v[200:203], v155 offset:52224
	ds_read_b128 v[204:207], v155 offset:53248
	ds_read_b128 v[208:211], v155 offset:54272
	ds_read_b128 v[212:215], v155 offset:55296
	ds_read_b128 v[216:219], v155 offset:56320
	global_load_lds_dwordx4 v[148:149], off
	s_add_i32 m0, s38, 0x2000
	s_add_u32 s36, s36, 0x100080
	v_lshl_add_u64 v[148:149], v[220:221], 0, s[6:7]
	s_addc_u32 s37, s37, 0
	s_add_i32 s38, s56, s13
	global_load_lds_dwordx4 v[148:149], off
	v_lshl_add_u64 v[148:149], s[36:37], 0, v[134:135]
	s_mov_b32 m0, s38
	s_nop 0
	global_load_lds_dwordx4 v[148:149], off
	v_lshl_add_u64 v[148:149], s[36:37], 0, v[130:131]
	s_add_i32 m0, s38, 0x2000
	s_nop 0
	global_load_lds_dwordx4 v[148:149], off
	v_lshl_add_u64 v[148:149], v[224:225], 0, s[6:7]
	s_mov_b32 m0, s41
	s_nop 0
	global_load_lds_dwordx4 v[148:149], off
	v_lshl_add_u64 v[148:149], v[226:227], 0, s[6:7]
	s_mov_b32 m0, s42
	s_nop 0
	global_load_lds_dwordx4 v[148:149], off
	s_waitcnt vmcnt(8)
	s_waitcnt lgkmcnt(0)
	s_barrier
	v_mfma_f32_16x16x32_bf16 v[62:65], v[156:159], v[188:191], v[62:65]
	v_mfma_f32_16x16x32_bf16 v[58:61], v[164:167], v[188:191], v[58:61]
	v_mfma_f32_16x16x32_bf16 v[54:57], v[156:159], v[196:199], v[54:57]
	v_mfma_f32_16x16x32_bf16 v[50:53], v[164:167], v[196:199], v[50:53]
	v_mfma_f32_16x16x32_bf16 v[30:33], v[156:159], v[204:207], v[30:33]
	v_mfma_f32_16x16x32_bf16 v[26:29], v[164:167], v[204:207], v[26:29]
	v_mfma_f32_16x16x32_bf16 v[22:25], v[156:159], v[212:215], v[22:25]
	v_mfma_f32_16x16x32_bf16 v[18:21], v[164:167], v[212:215], v[18:21]
	v_mfma_f32_16x16x32_bf16 v[62:65], v[160:163], v[192:195], v[62:65]
	v_mfma_f32_16x16x32_bf16 v[58:61], v[168:171], v[192:195], v[58:61]
	v_mfma_f32_16x16x32_bf16 v[54:57], v[160:163], v[200:203], v[54:57]
	v_mfma_f32_16x16x32_bf16 v[50:53], v[168:171], v[200:203], v[50:53]
	v_mfma_f32_16x16x32_bf16 v[30:33], v[160:163], v[208:211], v[30:33]
	v_mfma_f32_16x16x32_bf16 v[26:29], v[168:171], v[208:211], v[26:29]
	v_mfma_f32_16x16x32_bf16 v[22:25], v[160:163], v[216:219], v[22:25]
	v_mfma_f32_16x16x32_bf16 v[18:21], v[168:171], v[216:219], v[18:21]
	v_mfma_f32_16x16x32_bf16 v[46:49], v[172:175], v[188:191], v[46:49]
	v_mfma_f32_16x16x32_bf16 v[42:45], v[180:183], v[188:191], v[42:45]
	v_mfma_f32_16x16x32_bf16 v[38:41], v[172:175], v[196:199], v[38:41]
	v_mfma_f32_16x16x32_bf16 v[34:37], v[180:183], v[196:199], v[34:37]
	v_mfma_f32_16x16x32_bf16 v[14:17], v[172:175], v[204:207], v[14:17]
	v_mfma_f32_16x16x32_bf16 v[10:13], v[180:183], v[204:207], v[10:13]
	v_mfma_f32_16x16x32_bf16 v[6:9], v[172:175], v[212:215], v[6:9]
	v_mfma_f32_16x16x32_bf16 v[2:5], v[180:183], v[212:215], v[2:5]
	v_mfma_f32_16x16x32_bf16 v[46:49], v[176:179], v[192:195], v[46:49]
	v_mfma_f32_16x16x32_bf16 v[42:45], v[184:187], v[192:195], v[42:45]
	v_mfma_f32_16x16x32_bf16 v[38:41], v[176:179], v[200:203], v[38:41]
	v_mfma_f32_16x16x32_bf16 v[34:37], v[184:187], v[200:203], v[34:37]
	v_mfma_f32_16x16x32_bf16 v[14:17], v[176:179], v[208:211], v[14:17]
	v_mfma_f32_16x16x32_bf16 v[10:13], v[184:187], v[208:211], v[10:13]
	v_mfma_f32_16x16x32_bf16 v[6:9], v[176:179], v[216:219], v[6:9]
	v_mfma_f32_16x16x32_bf16 v[2:5], v[184:187], v[216:219], v[2:5]
	s_barrier
	s_add_i32 s54, s54, 2
	s_add_u32 s26, s26, 0x100
	s_addc_u32 s27, s27, 0
	s_add_u32 s52, s52, 0x100
	s_addc_u32 s53, s53, 0
	s_cmp_gt_u32 s54, 61
	s_cbranch_scc0 .LBB0_788
	s_and_b64 vcc, exec, s[8:9]
	s_cbranch_vccz .LBB0_791
	s_barrier

.Lpeeld:
	ds_read_b128 v[130:133], v207
	ds_read_b128 v[134:137], v207 offset:1024
	ds_read_b128 v[138:141], v207 offset:2048
	ds_read_b128 v[142:145], v207 offset:3072
	ds_read_b128 v[146:149], v208
	ds_read_b128 v[172:175], v208 offset:1024
	ds_read_b128 v[176:179], v208 offset:2048
	ds_read_b128 v[210:213], v208 offset:3072
	s_add_u32 s10, s8, 0xffd50080
	s_addc_u32 s11, s9, -1
	s_cmpk_eq_i32 s16, 0xa8
	s_cselect_b32 s13, s25, s11
	s_cselect_b32 s12, s24, s10
	s_cselect_b32 s11, s41, s15
	s_cselect_b32 s10, s40, s14
	v_lshl_add_u64 v[180:181], s[8:9], 0, v[166:167]
	s_add_i32 m0, s48, 0xc000
	ds_read_b128 v[214:217], v202
	ds_read_b128 v[218:221], v202 offset:1024
	ds_read_b128 v[224:227], v202 offset:2048
	ds_read_b128 v[228:231], v202 offset:3072
	ds_read_b128 v[232:235], v202 offset:4096
	ds_read_b128 v[236:239], v202 offset:5120
	ds_read_b128 v[240:243], v202 offset:6144
	ds_read_b128 v[244:247], v202 offset:7168
	global_load_lds_dwordx4 v[180:181], off
	v_lshl_add_u64 v[180:181], s[8:9], 0, v[168:169]
	s_add_i32 m0, s48, 0xe000
	s_nop 0
	global_load_lds_dwordx4 v[180:181], off
	s_waitcnt vmcnt(8)
	s_waitcnt lgkmcnt(0)
	s_barrier
	v_mfma_f32_16x16x32_bf16 v[90:93], v[130:133], v[214:217], 0
	v_mfma_f32_16x16x32_bf16 v[74:77], v[138:141], v[214:217], 0
	v_mfma_f32_16x16x32_bf16 v[46:49], v[130:133], v[224:227], 0
	v_mfma_f32_16x16x32_bf16 v[42:45], v[138:141], v[224:227], 0
	v_mfma_f32_16x16x32_bf16 v[126:129], v[130:133], v[232:235], 0
	v_mfma_f32_16x16x32_bf16 v[122:125], v[138:141], v[232:235], 0
	v_mfma_f32_16x16x32_bf16 v[110:113], v[130:133], v[240:243], 0
	v_mfma_f32_16x16x32_bf16 v[106:109], v[138:141], v[240:243], 0
	v_mfma_f32_16x16x32_bf16 v[90:93], v[134:137], v[218:221], v[90:93]
	v_mfma_f32_16x16x32_bf16 v[74:77], v[142:145], v[218:221], v[74:77]
	v_mfma_f32_16x16x32_bf16 v[46:49], v[134:137], v[228:231], v[46:49]
	v_mfma_f32_16x16x32_bf16 v[42:45], v[142:145], v[228:231], v[42:45]
	v_mfma_f32_16x16x32_bf16 v[126:129], v[134:137], v[236:239], v[126:129]
	v_mfma_f32_16x16x32_bf16 v[122:125], v[142:145], v[236:239], v[122:125]
	v_mfma_f32_16x16x32_bf16 v[110:113], v[134:137], v[244:247], v[110:113]
	v_mfma_f32_16x16x32_bf16 v[106:109], v[142:145], v[244:247], v[106:109]
	v_mfma_f32_16x16x32_bf16 v[70:73], v[146:149], v[214:217], 0
	v_mfma_f32_16x16x32_bf16 v[66:69], v[176:179], v[214:217], 0
	v_mfma_f32_16x16x32_bf16 v[34:37], v[146:149], v[224:227], 0
	v_mfma_f32_16x16x32_bf16 v[38:41], v[176:179], v[224:227], 0
	v_mfma_f32_16x16x32_bf16 v[118:121], v[146:149], v[232:235], 0
	v_mfma_f32_16x16x32_bf16 v[114:117], v[176:179], v[232:235], 0
	v_mfma_f32_16x16x32_bf16 v[102:105], v[146:149], v[240:243], 0
	v_mfma_f32_16x16x32_bf16 v[98:101], v[176:179], v[240:243], 0
	v_mfma_f32_16x16x32_bf16 v[70:73], v[172:175], v[218:221], v[70:73]
	v_mfma_f32_16x16x32_bf16 v[66:69], v[210:213], v[218:221], v[66:69]
	v_mfma_f32_16x16x32_bf16 v[34:37], v[172:175], v[228:231], v[34:37]
	v_mfma_f32_16x16x32_bf16 v[38:41], v[210:213], v[228:231], v[38:41]
	v_mfma_f32_16x16x32_bf16 v[118:121], v[172:175], v[236:239], v[118:121]
	v_mfma_f32_16x16x32_bf16 v[114:117], v[210:213], v[236:239], v[114:117]
	v_mfma_f32_16x16x32_bf16 v[102:105], v[172:175], v[244:247], v[102:105]
	v_mfma_f32_16x16x32_bf16 v[98:101], v[210:213], v[244:247], v[98:101]
	s_barrier
	s_add_i32 s17, s57, s46
	v_lshl_add_u64 v[180:181], s[10:11], 0, v[150:151]
	s_mov_b32 m0, s17
	ds_read_b128 v[214:217], v202 offset:16384
	ds_read_b128 v[218:221], v202 offset:17408
	ds_read_b128 v[224:227], v202 offset:18432
	ds_read_b128 v[228:231], v202 offset:19456
	ds_read_b128 v[232:235], v202 offset:20480
	ds_read_b128 v[236:239], v202 offset:21504
	ds_read_b128 v[240:243], v202 offset:22528
	ds_read_b128 v[244:247], v202 offset:23552
	global_load_lds_dwordx4 v[180:181], off
	s_add_i32 m0, s17, 0x2000
	s_add_u32 s18, s10, 0x2b0000
	v_lshl_add_u64 v[248:249], s[10:11], 0, v[152:153]
	s_addc_u32 s19, s11, 0
	s_add_i32 s17, s58, s46
	global_load_lds_dwordx4 v[248:249], off
	v_lshl_add_u64 v[250:251], s[18:19], 0, v[150:151]
	s_mov_b32 m0, s17
	v_lshl_add_u64 v[252:253], s[12:13], 0, v[152:153]
	global_load_lds_dwordx4 v[250:251], off
	v_lshl_add_u64 v[250:251], s[18:19], 0, v[152:153]
	s_add_i32 m0, s17, 0x2000
	s_nop 0
	global_load_lds_dwordx4 v[250:251], off
	v_lshl_add_u64 v[250:251], s[12:13], 0, v[150:151]
	s_mov_b32 m0, s48
	s_nop 0
	global_load_lds_dwordx4 v[250:251], off
	s_mov_b32 m0, s49
	s_nop 0
	global_load_lds_dwordx4 v[252:253], off
	s_waitcnt vmcnt(8)
	s_waitcnt lgkmcnt(0)
	s_barrier
	v_mfma_f32_16x16x32_bf16 v[94:97], v[130:133], v[214:217], 0
	v_mfma_f32_16x16x32_bf16 v[86:89], v[138:141], v[214:217], 0
	v_mfma_f32_16x16x32_bf16 v[82:85], v[130:133], v[224:227], 0
	v_mfma_f32_16x16x32_bf16 v[78:81], v[138:141], v[224:227], 0
	v_mfma_f32_16x16x32_bf16 v[30:33], v[130:133], v[232:235], 0
	v_mfma_f32_16x16x32_bf16 v[26:29], v[138:141], v[232:235], 0
	v_mfma_f32_16x16x32_bf16 v[22:25], v[130:133], v[240:243], 0
	v_mfma_f32_16x16x32_bf16 v[18:21], v[138:141], v[240:243], 0
	v_mfma_f32_16x16x32_bf16 v[94:97], v[134:137], v[218:221], v[94:97]
	v_mfma_f32_16x16x32_bf16 v[86:89], v[142:145], v[218:221], v[86:89]
	v_mfma_f32_16x16x32_bf16 v[82:85], v[134:137], v[228:231], v[82:85]
	v_mfma_f32_16x16x32_bf16 v[78:81], v[142:145], v[228:231], v[78:81]
	v_mfma_f32_16x16x32_bf16 v[30:33], v[134:137], v[236:239], v[30:33]
	v_mfma_f32_16x16x32_bf16 v[26:29], v[142:145], v[236:239], v[26:29]
	v_mfma_f32_16x16x32_bf16 v[22:25], v[134:137], v[244:247], v[22:25]
	v_mfma_f32_16x16x32_bf16 v[18:21], v[142:145], v[244:247], v[18:21]
	v_mfma_f32_16x16x32_bf16 v[62:65], v[146:149], v[214:217], 0
	v_mfma_f32_16x16x32_bf16 v[58:61], v[176:179], v[214:217], 0
	v_mfma_f32_16x16x32_bf16 v[54:57], v[146:149], v[224:227], 0
	v_mfma_f32_16x16x32_bf16 v[50:53], v[176:179], v[224:227], 0
	v_mfma_f32_16x16x32_bf16 v[14:17], v[146:149], v[232:235], 0
	v_mfma_f32_16x16x32_bf16 v[6:9], v[176:179], v[232:235], 0
	v_mfma_f32_16x16x32_bf16 v[10:13], v[146:149], v[240:243], 0
	v_mfma_f32_16x16x32_bf16 v[2:5], v[176:179], v[240:243], 0
	v_mfma_f32_16x16x32_bf16 v[62:65], v[172:175], v[218:221], v[62:65]
	v_mfma_f32_16x16x32_bf16 v[58:61], v[210:213], v[218:221], v[58:61]
	v_mfma_f32_16x16x32_bf16 v[54:57], v[172:175], v[228:231], v[54:57]
	v_mfma_f32_16x16x32_bf16 v[50:53], v[210:213], v[228:231], v[50:53]
	v_mfma_f32_16x16x32_bf16 v[14:17], v[172:175], v[236:239], v[14:17]
	v_mfma_f32_16x16x32_bf16 v[6:9], v[210:213], v[236:239], v[6:9]
	v_mfma_f32_16x16x32_bf16 v[10:13], v[172:175], v[244:247], v[10:13]
	v_mfma_f32_16x16x32_bf16 v[2:5], v[210:213], v[244:247], v[2:5]
	s_barrier
	s_add_i32 s17, 0, 0x18000
	s_add_i32 s18, 0, 0x1c000
	v_add_u32_e32 v142, s17, v182
	v_add_u32_e32 v154, s18, v182
	ds_read_b128 v[130:133], v142
	ds_read_b128 v[134:137], v142 offset:1024
	ds_read_b128 v[138:141], v142 offset:2048
	ds_read_b128 v[142:145], v142 offset:3072
	ds_read_b128 v[146:149], v154
	ds_read_b128 v[172:175], v154 offset:1024
	ds_read_b128 v[176:179], v154 offset:2048
	ds_read_b128 v[210:213], v154 offset:3072
	s_add_u32 s12, s12, 0x2b0000
	s_addc_u32 s13, s13, 0
	s_mov_b32 m0, s50
	v_lshl_add_u64 v[188:189], s[12:13], 0, v[150:151]
	ds_read_b128 v[214:217], v202 offset:32768
	ds_read_b128 v[218:221], v202 offset:33792
	ds_read_b128 v[224:227], v202 offset:34816
	ds_read_b128 v[228:231], v202 offset:35840
	ds_read_b128 v[232:235], v202 offset:36864
	ds_read_b128 v[236:239], v202 offset:37888
	ds_read_b128 v[240:243], v202 offset:38912
	ds_read_b128 v[244:247], v202 offset:39936
	global_load_lds_dwordx4 v[188:189], off
	v_lshl_add_u64 v[188:189], s[12:13], 0, v[152:153]
	s_mov_b32 m0, s51
	s_nop 0
	global_load_lds_dwordx4 v[188:189], off
	s_waitcnt vmcnt(8)
	s_waitcnt lgkmcnt(0)
	s_barrier
	v_mfma_f32_16x16x32_bf16 v[90:93], v[130:133], v[214:217], v[90:93]
	v_mfma_f32_16x16x32_bf16 v[74:77], v[138:141], v[214:217], v[74:77]
	v_mfma_f32_16x16x32_bf16 v[46:49], v[130:133], v[224:227], v[46:49]
	v_mfma_f32_16x16x32_bf16 v[42:45], v[138:141], v[224:227], v[42:45]
	v_mfma_f32_16x16x32_bf16 v[126:129], v[130:133], v[232:235], v[126:129]
	v_mfma_f32_16x16x32_bf16 v[122:125], v[138:141], v[232:235], v[122:125]
	v_mfma_f32_16x16x32_bf16 v[110:113], v[130:133], v[240:243], v[110:113]
	v_mfma_f32_16x16x32_bf16 v[106:109], v[138:141], v[240:243], v[106:109]
	v_mfma_f32_16x16x32_bf16 v[90:93], v[134:137], v[218:221], v[90:93]
	v_mfma_f32_16x16x32_bf16 v[74:77], v[142:145], v[218:221], v[74:77]
	v_mfma_f32_16x16x32_bf16 v[46:49], v[134:137], v[228:231], v[46:49]
	v_mfma_f32_16x16x32_bf16 v[42:45], v[142:145], v[228:231], v[42:45]
	v_mfma_f32_16x16x32_bf16 v[126:129], v[134:137], v[236:239], v[126:129]
	v_mfma_f32_16x16x32_bf16 v[122:125], v[142:145], v[236:239], v[122:125]
	v_mfma_f32_16x16x32_bf16 v[110:113], v[134:137], v[244:247], v[110:113]
	v_mfma_f32_16x16x32_bf16 v[106:109], v[142:145], v[244:247], v[106:109]
	v_mfma_f32_16x16x32_bf16 v[70:73], v[146:149], v[214:217], v[70:73]
	v_mfma_f32_16x16x32_bf16 v[66:69], v[176:179], v[214:217], v[66:69]
	v_mfma_f32_16x16x32_bf16 v[34:37], v[146:149], v[224:227], v[34:37]
	v_mfma_f32_16x16x32_bf16 v[38:41], v[176:179], v[224:227], v[38:41]
	v_mfma_f32_16x16x32_bf16 v[118:121], v[146:149], v[232:235], v[118:121]
	v_mfma_f32_16x16x32_bf16 v[114:117], v[176:179], v[232:235], v[114:117]
	v_mfma_f32_16x16x32_bf16 v[102:105], v[146:149], v[240:243], v[102:105]
	v_mfma_f32_16x16x32_bf16 v[98:101], v[176:179], v[240:243], v[98:101]
	v_mfma_f32_16x16x32_bf16 v[70:73], v[172:175], v[218:221], v[70:73]
	v_mfma_f32_16x16x32_bf16 v[66:69], v[210:213], v[218:221], v[66:69]
	v_mfma_f32_16x16x32_bf16 v[34:37], v[172:175], v[228:231], v[34:37]
	v_mfma_f32_16x16x32_bf16 v[38:41], v[210:213], v[228:231], v[38:41]
	v_mfma_f32_16x16x32_bf16 v[118:121], v[172:175], v[236:239], v[118:121]
	v_mfma_f32_16x16x32_bf16 v[114:117], v[210:213], v[236:239], v[114:117]
	v_mfma_f32_16x16x32_bf16 v[102:105], v[172:175], v[244:247], v[102:105]
	v_mfma_f32_16x16x32_bf16 v[98:101], v[210:213], v[244:247], v[98:101]
	s_barrier
	s_add_i32 s12, s17, s46
	v_lshl_add_u64 v[180:181], v[180:181], 0, s[30:31]
	s_mov_b32 m0, s12
	ds_read_b128 v[214:217], v202 offset:49152
	ds_read_b128 v[218:221], v202 offset:50176
	ds_read_b128 v[224:227], v202 offset:51200
	ds_read_b128 v[228:231], v202 offset:52224
	ds_read_b128 v[232:235], v202 offset:53248
	ds_read_b128 v[236:239], v202 offset:54272
	ds_read_b128 v[240:243], v202 offset:55296
	ds_read_b128 v[244:247], v202 offset:56320
	global_load_lds_dwordx4 v[180:181], off
	s_add_i32 m0, s12, 0x2000
	s_add_u32 s10, s10, 0x2b0080
	v_lshl_add_u64 v[180:181], v[248:249], 0, s[30:31]
	s_addc_u32 s11, s11, 0
	s_add_i32 s12, s18, s46
	global_load_lds_dwordx4 v[180:181], off
	v_lshl_add_u64 v[180:181], s[10:11], 0, v[150:151]
	s_mov_b32 m0, s12
	s_nop 0
	global_load_lds_dwordx4 v[180:181], off
	v_lshl_add_u64 v[180:181], s[10:11], 0, v[152:153]
	s_add_i32 m0, s12, 0x2000
	s_nop 0
	global_load_lds_dwordx4 v[180:181], off
	v_lshl_add_u64 v[180:181], v[250:251], 0, s[30:31]
	s_mov_b32 m0, s52
	s_nop 0
	global_load_lds_dwordx4 v[180:181], off
	v_lshl_add_u64 v[180:181], v[252:253], 0, s[30:31]
	s_mov_b32 m0, s53
	s_nop 0
	global_load_lds_dwordx4 v[180:181], off
	s_waitcnt vmcnt(8)
	s_waitcnt lgkmcnt(0)
	s_barrier
	v_mfma_f32_16x16x32_bf16 v[94:97], v[130:133], v[214:217], v[94:97]
	v_mfma_f32_16x16x32_bf16 v[86:89], v[138:141], v[214:217], v[86:89]
	v_mfma_f32_16x16x32_bf16 v[82:85], v[130:133], v[224:227], v[82:85]
	v_mfma_f32_16x16x32_bf16 v[78:81], v[138:141], v[224:227], v[78:81]
	v_mfma_f32_16x16x32_bf16 v[30:33], v[130:133], v[232:235], v[30:33]
	v_mfma_f32_16x16x32_bf16 v[26:29], v[138:141], v[232:235], v[26:29]
	v_mfma_f32_16x16x32_bf16 v[22:25], v[130:133], v[240:243], v[22:25]
	v_mfma_f32_16x16x32_bf16 v[18:21], v[138:141], v[240:243], v[18:21]
	v_mfma_f32_16x16x32_bf16 v[94:97], v[134:137], v[218:221], v[94:97]
	v_mfma_f32_16x16x32_bf16 v[86:89], v[142:145], v[218:221], v[86:89]
	v_mfma_f32_16x16x32_bf16 v[82:85], v[134:137], v[228:231], v[82:85]
	v_mfma_f32_16x16x32_bf16 v[78:81], v[142:145], v[228:231], v[78:81]
	v_mfma_f32_16x16x32_bf16 v[30:33], v[134:137], v[236:239], v[30:33]
	v_mfma_f32_16x16x32_bf16 v[26:29], v[142:145], v[236:239], v[26:29]
	v_mfma_f32_16x16x32_bf16 v[22:25], v[134:137], v[244:247], v[22:25]
	v_mfma_f32_16x16x32_bf16 v[18:21], v[142:145], v[244:247], v[18:21]
	v_mfma_f32_16x16x32_bf16 v[62:65], v[146:149], v[214:217], v[62:65]
	v_mfma_f32_16x16x32_bf16 v[58:61], v[176:179], v[214:217], v[58:61]
	v_mfma_f32_16x16x32_bf16 v[54:57], v[146:149], v[224:227], v[54:57]
	v_mfma_f32_16x16x32_bf16 v[50:53], v[176:179], v[224:227], v[50:53]
	v_mfma_f32_16x16x32_bf16 v[14:17], v[146:149], v[232:235], v[14:17]
	v_mfma_f32_16x16x32_bf16 v[6:9], v[176:179], v[232:235], v[6:9]
	v_mfma_f32_16x16x32_bf16 v[10:13], v[146:149], v[240:243], v[10:13]
	v_mfma_f32_16x16x32_bf16 v[2:5], v[176:179], v[240:243], v[2:5]
	v_mfma_f32_16x16x32_bf16 v[62:65], v[172:175], v[218:221], v[62:65]
	v_mfma_f32_16x16x32_bf16 v[58:61], v[210:213], v[218:221], v[58:61]
	v_mfma_f32_16x16x32_bf16 v[54:57], v[172:175], v[228:231], v[54:57]
	v_mfma_f32_16x16x32_bf16 v[50:53], v[210:213], v[228:231], v[50:53]
	v_mfma_f32_16x16x32_bf16 v[14:17], v[172:175], v[236:239], v[14:17]
	v_mfma_f32_16x16x32_bf16 v[6:9], v[210:213], v[236:239], v[6:9]
	v_mfma_f32_16x16x32_bf16 v[10:13], v[172:175], v[244:247], v[10:13]
	v_mfma_f32_16x16x32_bf16 v[2:5], v[210:213], v[244:247], v[2:5]
	s_barrier
	s_add_i32 s16, s16, 2
	s_add_u32 s8, s8, 0x100
	s_addc_u32 s9, s9, 0
	s_add_u32 s14, s14, 0x100
	s_addc_u32 s15, s15, 0
.LBB0_1040:
	ds_read_b128 v[130:133], v207
	ds_read_b128 v[134:137], v207 offset:1024
	ds_read_b128 v[138:141], v207 offset:2048
	ds_read_b128 v[142:145], v207 offset:3072
	ds_read_b128 v[146:149], v208
	ds_read_b128 v[172:175], v208 offset:1024
	ds_read_b128 v[176:179], v208 offset:2048
	ds_read_b128 v[210:213], v208 offset:3072
	s_add_u32 s10, s8, 0xffd50080
	s_addc_u32 s11, s9, -1
	s_cmpk_eq_i32 s16, 0xa8
	s_cselect_b32 s13, s25, s11
	s_cselect_b32 s12, s24, s10
	s_cselect_b32 s11, s41, s15
	s_cselect_b32 s10, s40, s14
	v_lshl_add_u64 v[180:181], s[8:9], 0, v[166:167]
	s_add_i32 m0, s48, 0xc000
	ds_read_b128 v[214:217], v202
	ds_read_b128 v[218:221], v202 offset:1024
	ds_read_b128 v[224:227], v202 offset:2048
	ds_read_b128 v[228:231], v202 offset:3072
	ds_read_b128 v[232:235], v202 offset:4096
	ds_read_b128 v[236:239], v202 offset:5120
	ds_read_b128 v[240:243], v202 offset:6144
	ds_read_b128 v[244:247], v202 offset:7168
	global_load_lds_dwordx4 v[180:181], off
	v_lshl_add_u64 v[180:181], s[8:9], 0, v[168:169]
	s_add_i32 m0, s48, 0xe000
	s_nop 0
	global_load_lds_dwordx4 v[180:181], off
	s_waitcnt vmcnt(8)
	s_waitcnt lgkmcnt(0)
	s_barrier
	v_mfma_f32_16x16x32_bf16 v[90:93], v[130:133], v[214:217], v[90:93]
	v_mfma_f32_16x16x32_bf16 v[74:77], v[138:141], v[214:217], v[74:77]
	v_mfma_f32_16x16x32_bf16 v[46:49], v[130:133], v[224:227], v[46:49]
	v_mfma_f32_16x16x32_bf16 v[42:45], v[138:141], v[224:227], v[42:45]
	v_mfma_f32_16x16x32_bf16 v[126:129], v[130:133], v[232:235], v[126:129]
	v_mfma_f32_16x16x32_bf16 v[122:125], v[138:141], v[232:235], v[122:125]
	v_mfma_f32_16x16x32_bf16 v[110:113], v[130:133], v[240:243], v[110:113]
	v_mfma_f32_16x16x32_bf16 v[106:109], v[138:141], v[240:243], v[106:109]
	v_mfma_f32_16x16x32_bf16 v[90:93], v[134:137], v[218:221], v[90:93]
	v_mfma_f32_16x16x32_bf16 v[74:77], v[142:145], v[218:221], v[74:77]
	v_mfma_f32_16x16x32_bf16 v[46:49], v[134:137], v[228:231], v[46:49]
	v_mfma_f32_16x16x32_bf16 v[42:45], v[142:145], v[228:231], v[42:45]
	v_mfma_f32_16x16x32_bf16 v[126:129], v[134:137], v[236:239], v[126:129]
	v_mfma_f32_16x16x32_bf16 v[122:125], v[142:145], v[236:239], v[122:125]
	v_mfma_f32_16x16x32_bf16 v[110:113], v[134:137], v[244:247], v[110:113]
	v_mfma_f32_16x16x32_bf16 v[106:109], v[142:145], v[244:247], v[106:109]
	v_mfma_f32_16x16x32_bf16 v[70:73], v[146:149], v[214:217], v[70:73]
	v_mfma_f32_16x16x32_bf16 v[66:69], v[176:179], v[214:217], v[66:69]
	v_mfma_f32_16x16x32_bf16 v[34:37], v[146:149], v[224:227], v[34:37]
	v_mfma_f32_16x16x32_bf16 v[38:41], v[176:179], v[224:227], v[38:41]
	v_mfma_f32_16x16x32_bf16 v[118:121], v[146:149], v[232:235], v[118:121]
	v_mfma_f32_16x16x32_bf16 v[114:117], v[176:179], v[232:235], v[114:117]
	v_mfma_f32_16x16x32_bf16 v[102:105], v[146:149], v[240:243], v[102:105]
	v_mfma_f32_16x16x32_bf16 v[98:101], v[176:179], v[240:243], v[98:101]
	v_mfma_f32_16x16x32_bf16 v[70:73], v[172:175], v[218:221], v[70:73]
	v_mfma_f32_16x16x32_bf16 v[66:69], v[210:213], v[218:221], v[66:69]
	v_mfma_f32_16x16x32_bf16 v[34:37], v[172:175], v[228:231], v[34:37]
	v_mfma_f32_16x16x32_bf16 v[38:41], v[210:213], v[228:231], v[38:41]
	v_mfma_f32_16x16x32_bf16 v[118:121], v[172:175], v[236:239], v[118:121]
	v_mfma_f32_16x16x32_bf16 v[114:117], v[210:213], v[236:239], v[114:117]
	v_mfma_f32_16x16x32_bf16 v[102:105], v[172:175], v[244:247], v[102:105]
	v_mfma_f32_16x16x32_bf16 v[98:101], v[210:213], v[244:247], v[98:101]
	s_barrier
	s_add_i32 s17, s57, s46
	v_lshl_add_u64 v[180:181], s[10:11], 0, v[150:151]
	s_mov_b32 m0, s17
	ds_read_b128 v[214:217], v202 offset:16384
	ds_read_b128 v[218:221], v202 offset:17408
	ds_read_b128 v[224:227], v202 offset:18432
	ds_read_b128 v[228:231], v202 offset:19456
	ds_read_b128 v[232:235], v202 offset:20480
	ds_read_b128 v[236:239], v202 offset:21504
	ds_read_b128 v[240:243], v202 offset:22528
	ds_read_b128 v[244:247], v202 offset:23552
	global_load_lds_dwordx4 v[180:181], off
	s_add_i32 m0, s17, 0x2000
	s_add_u32 s18, s10, 0x2b0000
	v_lshl_add_u64 v[248:249], s[10:11], 0, v[152:153]
	s_addc_u32 s19, s11, 0
	s_add_i32 s17, s58, s46
	global_load_lds_dwordx4 v[248:249], off
	v_lshl_add_u64 v[250:251], s[18:19], 0, v[150:151]
	s_mov_b32 m0, s17
	v_lshl_add_u64 v[252:253], s[12:13], 0, v[152:153]
	global_load_lds_dwordx4 v[250:251], off
	v_lshl_add_u64 v[250:251], s[18:19], 0, v[152:153]
	s_add_i32 m0, s17, 0x2000
	s_nop 0
	global_load_lds_dwordx4 v[250:251], off
	v_lshl_add_u64 v[250:251], s[12:13], 0, v[150:151]
	s_mov_b32 m0, s48
	s_nop 0
	global_load_lds_dwordx4 v[250:251], off
	s_mov_b32 m0, s49
	s_nop 0
	global_load_lds_dwordx4 v[252:253], off
	s_waitcnt vmcnt(8)
	s_waitcnt lgkmcnt(0)
	s_barrier
	v_mfma_f32_16x16x32_bf16 v[94:97], v[130:133], v[214:217], v[94:97]
	v_mfma_f32_16x16x32_bf16 v[86:89], v[138:141], v[214:217], v[86:89]
	v_mfma_f32_16x16x32_bf16 v[82:85], v[130:133], v[224:227], v[82:85]
	v_mfma_f32_16x16x32_bf16 v[78:81], v[138:141], v[224:227], v[78:81]
	v_mfma_f32_16x16x32_bf16 v[30:33], v[130:133], v[232:235], v[30:33]
	v_mfma_f32_16x16x32_bf16 v[26:29], v[138:141], v[232:235], v[26:29]
	v_mfma_f32_16x16x32_bf16 v[22:25], v[130:133], v[240:243], v[22:25]
	v_mfma_f32_16x16x32_bf16 v[18:21], v[138:141], v[240:243], v[18:21]
	v_mfma_f32_16x16x32_bf16 v[94:97], v[134:137], v[218:221], v[94:97]
	v_mfma_f32_16x16x32_bf16 v[86:89], v[142:145], v[218:221], v[86:89]
	v_mfma_f32_16x16x32_bf16 v[82:85], v[134:137], v[228:231], v[82:85]
	v_mfma_f32_16x16x32_bf16 v[78:81], v[142:145], v[228:231], v[78:81]
	v_mfma_f32_16x16x32_bf16 v[30:33], v[134:137], v[236:239], v[30:33]
	v_mfma_f32_16x16x32_bf16 v[26:29], v[142:145], v[236:239], v[26:29]
	v_mfma_f32_16x16x32_bf16 v[22:25], v[134:137], v[244:247], v[22:25]
	v_mfma_f32_16x16x32_bf16 v[18:21], v[142:145], v[244:247], v[18:21]
	v_mfma_f32_16x16x32_bf16 v[62:65], v[146:149], v[214:217], v[62:65]
	v_mfma_f32_16x16x32_bf16 v[58:61], v[176:179], v[214:217], v[58:61]
	v_mfma_f32_16x16x32_bf16 v[54:57], v[146:149], v[224:227], v[54:57]
	v_mfma_f32_16x16x32_bf16 v[50:53], v[176:179], v[224:227], v[50:53]
	v_mfma_f32_16x16x32_bf16 v[14:17], v[146:149], v[232:235], v[14:17]
	v_mfma_f32_16x16x32_bf16 v[6:9], v[176:179], v[232:235], v[6:9]
	v_mfma_f32_16x16x32_bf16 v[10:13], v[146:149], v[240:243], v[10:13]
	v_mfma_f32_16x16x32_bf16 v[2:5], v[176:179], v[240:243], v[2:5]
	v_mfma_f32_16x16x32_bf16 v[62:65], v[172:175], v[218:221], v[62:65]
	v_mfma_f32_16x16x32_bf16 v[58:61], v[210:213], v[218:221], v[58:61]
	v_mfma_f32_16x16x32_bf16 v[54:57], v[172:175], v[228:231], v[54:57]
	v_mfma_f32_16x16x32_bf16 v[50:53], v[210:213], v[228:231], v[50:53]
	v_mfma_f32_16x16x32_bf16 v[14:17], v[172:175], v[236:239], v[14:17]
	v_mfma_f32_16x16x32_bf16 v[6:9], v[210:213], v[236:239], v[6:9]
	v_mfma_f32_16x16x32_bf16 v[10:13], v[172:175], v[244:247], v[10:13]
	v_mfma_f32_16x16x32_bf16 v[2:5], v[210:213], v[244:247], v[2:5]
	s_barrier
	s_add_i32 s17, 0, 0x18000
	s_add_i32 s18, 0, 0x1c000
	v_add_u32_e32 v142, s17, v182
	v_add_u32_e32 v154, s18, v182
	ds_read_b128 v[130:133], v142
	ds_read_b128 v[134:137], v142 offset:1024
	ds_read_b128 v[138:141], v142 offset:2048
	ds_read_b128 v[142:145], v142 offset:3072
	ds_read_b128 v[146:149], v154
	ds_read_b128 v[172:175], v154 offset:1024
	ds_read_b128 v[176:179], v154 offset:2048
	ds_read_b128 v[210:213], v154 offset:3072
	s_add_u32 s12, s12, 0x2b0000
	s_addc_u32 s13, s13, 0
	s_mov_b32 m0, s50
	v_lshl_add_u64 v[188:189], s[12:13], 0, v[150:151]
	ds_read_b128 v[214:217], v202 offset:32768
	ds_read_b128 v[218:221], v202 offset:33792
	ds_read_b128 v[224:227], v202 offset:34816
	ds_read_b128 v[228:231], v202 offset:35840
	ds_read_b128 v[232:235], v202 offset:36864
	ds_read_b128 v[236:239], v202 offset:37888
	ds_read_b128 v[240:243], v202 offset:38912
	ds_read_b128 v[244:247], v202 offset:39936
	global_load_lds_dwordx4 v[188:189], off
	v_lshl_add_u64 v[188:189], s[12:13], 0, v[152:153]
	s_mov_b32 m0, s51
	s_nop 0
	global_load_lds_dwordx4 v[188:189], off
	s_waitcnt vmcnt(8)
	s_waitcnt lgkmcnt(0)
	s_barrier
	v_mfma_f32_16x16x32_bf16 v[90:93], v[130:133], v[214:217], v[90:93]
	v_mfma_f32_16x16x32_bf16 v[74:77], v[138:141], v[214:217], v[74:77]
	v_mfma_f32_16x16x32_bf16 v[46:49], v[130:133], v[224:227], v[46:49]
	v_mfma_f32_16x16x32_bf16 v[42:45], v[138:141], v[224:227], v[42:45]
	v_mfma_f32_16x16x32_bf16 v[126:129], v[130:133], v[232:235], v[126:129]
	v_mfma_f32_16x16x32_bf16 v[122:125], v[138:141], v[232:235], v[122:125]
	v_mfma_f32_16x16x32_bf16 v[110:113], v[130:133], v[240:243], v[110:113]
	v_mfma_f32_16x16x32_bf16 v[106:109], v[138:141], v[240:243], v[106:109]
	v_mfma_f32_16x16x32_bf16 v[90:93], v[134:137], v[218:221], v[90:93]
	v_mfma_f32_16x16x32_bf16 v[74:77], v[142:145], v[218:221], v[74:77]
	v_mfma_f32_16x16x32_bf16 v[46:49], v[134:137], v[228:231], v[46:49]
	v_mfma_f32_16x16x32_bf16 v[42:45], v[142:145], v[228:231], v[42:45]
	v_mfma_f32_16x16x32_bf16 v[126:129], v[134:137], v[236:239], v[126:129]
	v_mfma_f32_16x16x32_bf16 v[122:125], v[142:145], v[236:239], v[122:125]
	v_mfma_f32_16x16x32_bf16 v[110:113], v[134:137], v[244:247], v[110:113]
	v_mfma_f32_16x16x32_bf16 v[106:109], v[142:145], v[244:247], v[106:109]
	v_mfma_f32_16x16x32_bf16 v[70:73], v[146:149], v[214:217], v[70:73]
	v_mfma_f32_16x16x32_bf16 v[66:69], v[176:179], v[214:217], v[66:69]
	v_mfma_f32_16x16x32_bf16 v[34:37], v[146:149], v[224:227], v[34:37]
	v_mfma_f32_16x16x32_bf16 v[38:41], v[176:179], v[224:227], v[38:41]
	v_mfma_f32_16x16x32_bf16 v[118:121], v[146:149], v[232:235], v[118:121]
	v_mfma_f32_16x16x32_bf16 v[114:117], v[176:179], v[232:235], v[114:117]
	v_mfma_f32_16x16x32_bf16 v[102:105], v[146:149], v[240:243], v[102:105]
	v_mfma_f32_16x16x32_bf16 v[98:101], v[176:179], v[240:243], v[98:101]
	v_mfma_f32_16x16x32_bf16 v[70:73], v[172:175], v[218:221], v[70:73]
	v_mfma_f32_16x16x32_bf16 v[66:69], v[210:213], v[218:221], v[66:69]
	v_mfma_f32_16x16x32_bf16 v[34:37], v[172:175], v[228:231], v[34:37]
	v_mfma_f32_16x16x32_bf16 v[38:41], v[210:213], v[228:231], v[38:41]
	v_mfma_f32_16x16x32_bf16 v[118:121], v[172:175], v[236:239], v[118:121]
	v_mfma_f32_16x16x32_bf16 v[114:117], v[210:213], v[236:239], v[114:117]
	v_mfma_f32_16x16x32_bf16 v[102:105], v[172:175], v[244:247], v[102:105]
	v_mfma_f32_16x16x32_bf16 v[98:101], v[210:213], v[244:247], v[98:101]
	s_barrier
	s_add_i32 s12, s17, s46
	v_lshl_add_u64 v[180:181], v[180:181], 0, s[30:31]
	s_mov_b32 m0, s12
	ds_read_b128 v[214:217], v202 offset:49152
	ds_read_b128 v[218:221], v202 offset:50176
	ds_read_b128 v[224:227], v202 offset:51200
	ds_read_b128 v[228:231], v202 offset:52224
	ds_read_b128 v[232:235], v202 offset:53248
	ds_read_b128 v[236:239], v202 offset:54272
	ds_read_b128 v[240:243], v202 offset:55296
	ds_read_b128 v[244:247], v202 offset:56320
	global_load_lds_dwordx4 v[180:181], off
	s_add_i32 m0, s12, 0x2000
	s_add_u32 s10, s10, 0x2b0080
	v_lshl_add_u64 v[180:181], v[248:249], 0, s[30:31]
	s_addc_u32 s11, s11, 0
	s_add_i32 s12, s18, s46
	global_load_lds_dwordx4 v[180:181], off
	v_lshl_add_u64 v[180:181], s[10:11], 0, v[150:151]
	s_mov_b32 m0, s12
	s_nop 0
	global_load_lds_dwordx4 v[180:181], off
	v_lshl_add_u64 v[180:181], s[10:11], 0, v[152:153]
	s_add_i32 m0, s12, 0x2000
	s_nop 0
	global_load_lds_dwordx4 v[180:181], off
	v_lshl_add_u64 v[180:181], v[250:251], 0, s[30:31]
	s_mov_b32 m0, s52
	s_nop 0
	global_load_lds_dwordx4 v[180:181], off
	v_lshl_add_u64 v[180:181], v[252:253], 0, s[30:31]
	s_mov_b32 m0, s53
	s_nop 0
	global_load_lds_dwordx4 v[180:181], off
	s_waitcnt vmcnt(8)
	s_waitcnt lgkmcnt(0)
	s_barrier
	v_mfma_f32_16x16x32_bf16 v[94:97], v[130:133], v[214:217], v[94:97]
	v_mfma_f32_16x16x32_bf16 v[86:89], v[138:141], v[214:217], v[86:89]
	v_mfma_f32_16x16x32_bf16 v[82:85], v[130:133], v[224:227], v[82:85]
	v_mfma_f32_16x16x32_bf16 v[78:81], v[138:141], v[224:227], v[78:81]
	v_mfma_f32_16x16x32_bf16 v[30:33], v[130:133], v[232:235], v[30:33]
	v_mfma_f32_16x16x32_bf16 v[26:29], v[138:141], v[232:235], v[26:29]
	v_mfma_f32_16x16x32_bf16 v[22:25], v[130:133], v[240:243], v[22:25]
	v_mfma_f32_16x16x32_bf16 v[18:21], v[138:141], v[240:243], v[18:21]
	v_mfma_f32_16x16x32_bf16 v[94:97], v[134:137], v[218:221], v[94:97]
	v_mfma_f32_16x16x32_bf16 v[86:89], v[142:145], v[218:221], v[86:89]
	v_mfma_f32_16x16x32_bf16 v[82:85], v[134:137], v[228:231], v[82:85]
	v_mfma_f32_16x16x32_bf16 v[78:81], v[142:145], v[228:231], v[78:81]
	v_mfma_f32_16x16x32_bf16 v[30:33], v[134:137], v[236:239], v[30:33]
	v_mfma_f32_16x16x32_bf16 v[26:29], v[142:145], v[236:239], v[26:29]
	v_mfma_f32_16x16x32_bf16 v[22:25], v[134:137], v[244:247], v[22:25]
	v_mfma_f32_16x16x32_bf16 v[18:21], v[142:145], v[244:247], v[18:21]
	v_mfma_f32_16x16x32_bf16 v[62:65], v[146:149], v[214:217], v[62:65]
	v_mfma_f32_16x16x32_bf16 v[58:61], v[176:179], v[214:217], v[58:61]
	v_mfma_f32_16x16x32_bf16 v[54:57], v[146:149], v[224:227], v[54:57]
	v_mfma_f32_16x16x32_bf16 v[50:53], v[176:179], v[224:227], v[50:53]
	v_mfma_f32_16x16x32_bf16 v[14:17], v[146:149], v[232:235], v[14:17]
	v_mfma_f32_16x16x32_bf16 v[6:9], v[176:179], v[232:235], v[6:9]
	v_mfma_f32_16x16x32_bf16 v[10:13], v[146:149], v[240:243], v[10:13]
	v_mfma_f32_16x16x32_bf16 v[2:5], v[176:179], v[240:243], v[2:5]
	v_mfma_f32_16x16x32_bf16 v[62:65], v[172:175], v[218:221], v[62:65]
	v_mfma_f32_16x16x32_bf16 v[58:61], v[210:213], v[218:221], v[58:61]
	v_mfma_f32_16x16x32_bf16 v[54:57], v[172:175], v[228:231], v[54:57]
	v_mfma_f32_16x16x32_bf16 v[50:53], v[210:213], v[228:231], v[50:53]
	v_mfma_f32_16x16x32_bf16 v[14:17], v[172:175], v[236:239], v[14:17]
	v_mfma_f32_16x16x32_bf16 v[6:9], v[210:213], v[236:239], v[6:9]
	v_mfma_f32_16x16x32_bf16 v[10:13], v[172:175], v[244:247], v[10:13]
	v_mfma_f32_16x16x32_bf16 v[2:5], v[210:213], v[244:247], v[2:5]
	s_barrier
	s_add_i32 s16, s16, 2
	s_add_u32 s8, s8, 0x100
	s_addc_u32 s9, s9, 0
	s_add_u32 s14, s14, 0x100
	s_addc_u32 s15, s15, 0
	s_cmpk_gt_u32 s16, 0xa9
	s_cbranch_scc0 .LBB0_1040
	s_and_b64 vcc, exec, s[34:35]
	s_cbranch_vccz .LBB0_1043
	s_barrier
